# GEMM K-loops: LDS slot constants no longer rebuilt per iteration (M0 = reg + literal), vmcnt+lgkmcnt waits merged: 6 fewer loader SALU per iteration; on v104
# speedup vs baseline: 1.0124x; 1.0019x over previous
; #define PG8_STAGE(bufoff, gbase, voff) do { _Pragma("unroll") for (int _i = 0; _i < 2; ++_i) \
;         __builtin_amdgcn_global_load_lds((const unsigned*)((const char*)(gbase) + (voff)[_i]), (PG8_LAS unsigned*)(lds + (bufoff) + ldsw + _i * 8192), 16, 0, 0); } while (0)
; #define PG8_LDA(dst, b, h) do { _Pragma("unroll") for (int m = 0; m < 4; ++m) _Pragma("unroll") for (int k = 0; k < 2; ++k) dst[m][k] = *(const PG8_LAS bf16x8*)(lds + PG8_SA(b, h) + aoff + m * 2048 + k * 1024); } while (0)
; #define PG8_LDB(dst, b, h) do { _Pragma("unroll") for (int n = 0; n < 2; ++n) _Pragma("unroll") for (int k = 0; k < 2; ++k) dst[n][k] = *(const PG8_LAS bf16x8*)(lds + PG8_SB(b, h) + boff + n * 2048 + k * 1024); } while (0)
; #define PG8_MMA(ai, bj, At, Bt) do { __builtin_amdgcn_s_setprio(1); _Pragma("unroll") for (int m = 0; m < 4; ++m) _Pragma("unroll") for (int n = 0; n < 2; ++n) _Pragma("unroll") for (int k = 0; k < 2; ++k) \
;         acc[ai][bj][m][n] = __builtin_amdgcn_mfma_f32_16x16x32_bf16(Bt[n][k], At[m][k], acc[ai][bj][m][n], 0, 0, 0); __builtin_amdgcn_s_setprio(0); } while (0)
; #define PG8_WAIT_L(n) asm volatile("s_waitcnt lgkmcnt(" #n ")" ::: "memory")
; #define PG8_BAR __builtin_amdgcn_s_barrier()
; template <class Epi, class Sched, bool ALIGN_EPI = false, bool SP2 = false>
; __device__ __forceinline__ void gemm_phase(PG8_LAS unsigned char* lds, const Gemm g, const Sched& S, const Epi& E) {
;     ...
;             const char* a1 = cA + (size_t)(t + 1) * kstep;
;             const char* a2 = last ? nA : cA + (size_t)(t + 2) * kstep; const char* b2 = last ? nB : cB + (size_t)(t + 2) * kstep;
;             const char* a3 = a2 + kstep; const char* b3 = b2 + kstep;
;             if (last && has_next) S.a_ready(nxt);
;             if constexpr (SP2) {
;             const int rx = (relax && t == 0) ? 1 : 0;
;             PG8_STAGE(PG8_SA(1, 1), a1 + hstep, voffA); PG8_SCHED; PG8_LDB(B0, 0, 0); PG8_LDB(B1, 0, 1); PG8_SCHED; PG8_LDA(At, 0, 0);
;             PG8_WAIT_V8_UNLESS(rx); PG8_WAIT_L(0); PG8_BAR; PG8_MMA(0, 0, At, B0); PG8_MMA(0, 1, At, B1); PG8_BAR; PG8_SCHED;
;             PG8_STAGE(PG8_SB(0, 0), b2, voffB); PG8_STAGE(PG8_SB(0, 1), b2 + hstep, voffB); PG8_STAGE(PG8_SA(0, 0), a2, voffA); PG8_SCHED; PG8_LDA(At, 0, 1);
;             PG8_WAIT_V8_UNLESS(rx); PG8_WAIT_L(0); PG8_BAR; PG8_MMA(1, 0, At, B0); PG8_MMA(1, 1, At, B1); PG8_BAR; PG8_SCHED;
.LBB0_148:
	s_add_u32 s28, s0, vcc_lo
	s_addc_u32 s29, s1, vcc_hi
	s_add_u32 s30, s28, 0x100
	s_addc_u32 s31, s29, 0
	s_add_u32 s98, s28, 0x40080
	s_addc_u32 s99, s29, 0
	s_add_u32 s61, s58, vcc_lo
	s_addc_u32 s65, s59, vcc_hi
	s_cmp_eq_u32 vcc_lo, 0
	s_cselect_b64 s[28:29], -1, 0
	s_and_b64 s[66:67], s[42:43], s[28:29]
	s_cmpk_eq_i32 vcc_lo, 0x700
	s_cselect_b32 s31, s21, s31
	s_cselect_b32 s30, s34, s30
	s_cselect_b32 s29, s19, s65
	s_cselect_b32 s28, s41, s61
	ds_read_b128 v[144:147], v128
	ds_read_b128 v[148:151], v128 offset:1024
	ds_read_b128 v[152:155], v128 offset:2048
	ds_read_b128 v[156:159], v128 offset:3072
	ds_read_b128 v[160:163], v128 offset:16384
	ds_read_b128 v[164:167], v128 offset:17408
	ds_read_b128 v[168:171], v128 offset:18432
	ds_read_b128 v[174:177], v128 offset:19456
	ds_read_b128 v[178:181], v173
	ds_read_b128 v[182:185], v173 offset:1024
	ds_read_b128 v[186:189], v173 offset:2048
	ds_read_b128 v[204:207], v173 offset:3072
	ds_read_b128 v[208:211], v173 offset:4096
	ds_read_b128 v[212:215], v173 offset:5120
	ds_read_b128 v[216:219], v173 offset:6144
	s_add_i32 m0, s9, 0xc000
	s_and_b32 s70, s66, 1
	global_load_lds_dwordx4 v132, s[98:99]
	s_add_i32 m0, s9, 0xe000
	ds_read_b128 v[220:223], v173 offset:7168
	global_load_lds_dwordx4 v136, s[98:99]
	s_cmp_lg_i32 s70, 0
	s_cbranch_scc1 .Lpg8rx0
	s_waitcnt vmcnt(8)
.Lpg8rx0:
	s_waitcnt lgkmcnt(0)
	s_setprio 1
	s_barrier
	v_mfma_f32_16x16x32_bf16 v[124:127], v[144:147], v[178:181], v[124:127]
	v_mfma_f32_16x16x32_bf16 v[120:123], v[152:155], v[178:181], v[120:123]
	v_mfma_f32_16x16x32_bf16 v[108:111], v[144:147], v[186:189], v[108:111]
	v_mfma_f32_16x16x32_bf16 v[104:107], v[152:155], v[186:189], v[104:107]
	v_mfma_f32_16x16x32_bf16 v[92:95], v[144:147], v[208:211], v[92:95]
	v_mfma_f32_16x16x32_bf16 v[88:91], v[152:155], v[208:211], v[88:91]
	v_mfma_f32_16x16x32_bf16 v[76:79], v[144:147], v[216:219], v[76:79]
	v_mfma_f32_16x16x32_bf16 v[72:75], v[152:155], v[216:219], v[72:75]
	v_mfma_f32_16x16x32_bf16 v[124:127], v[148:151], v[182:185], v[124:127]
	v_mfma_f32_16x16x32_bf16 v[120:123], v[156:159], v[182:185], v[120:123]
	v_mfma_f32_16x16x32_bf16 v[108:111], v[148:151], v[204:207], v[108:111]
	v_mfma_f32_16x16x32_bf16 v[104:107], v[156:159], v[204:207], v[104:107]
	v_mfma_f32_16x16x32_bf16 v[92:95], v[148:151], v[212:215], v[92:95]
	v_mfma_f32_16x16x32_bf16 v[88:91], v[156:159], v[212:215], v[88:91]
	v_mfma_f32_16x16x32_bf16 v[76:79], v[148:151], v[220:223], v[76:79]
	v_mfma_f32_16x16x32_bf16 v[72:75], v[156:159], v[220:223], v[72:75]
	v_mfma_f32_16x16x32_bf16 v[116:119], v[160:163], v[178:181], v[116:119]
	v_mfma_f32_16x16x32_bf16 v[112:115], v[168:171], v[178:181], v[112:115]
	v_mfma_f32_16x16x32_bf16 v[100:103], v[160:163], v[186:189], v[100:103]
	v_mfma_f32_16x16x32_bf16 v[96:99], v[168:171], v[186:189], v[96:99]
	v_mfma_f32_16x16x32_bf16 v[84:87], v[160:163], v[208:211], v[84:87]
	v_mfma_f32_16x16x32_bf16 v[80:83], v[168:171], v[208:211], v[80:83]
	v_mfma_f32_16x16x32_bf16 v[68:71], v[160:163], v[216:219], v[68:71]
	v_mfma_f32_16x16x32_bf16 v[64:67], v[168:171], v[216:219], v[64:67]
	v_mfma_f32_16x16x32_bf16 v[116:119], v[164:167], v[182:185], v[116:119]
	v_mfma_f32_16x16x32_bf16 v[112:115], v[174:177], v[182:185], v[112:115]
	v_mfma_f32_16x16x32_bf16 v[100:103], v[164:167], v[204:207], v[100:103]
	v_mfma_f32_16x16x32_bf16 v[96:99], v[174:177], v[204:207], v[96:99]
	v_mfma_f32_16x16x32_bf16 v[84:87], v[164:167], v[212:215], v[84:87]
	v_mfma_f32_16x16x32_bf16 v[80:83], v[174:177], v[212:215], v[80:83]
	v_mfma_f32_16x16x32_bf16 v[68:71], v[164:167], v[220:223], v[68:71]
	v_mfma_f32_16x16x32_bf16 v[64:67], v[174:177], v[220:223], v[64:67]
	s_setprio 0
	s_barrier
	ds_read_b128 v[178:181], v173 offset:16384
	ds_read_b128 v[182:185], v173 offset:17408
	s_add_u32 s66, s28, 0x40000
	s_addc_u32 s67, s29, 0
	s_add_i32 m0, s46, 0x10000
	ds_read_b128 v[186:189], v173 offset:18432
	global_load_lds_dwordx4 v134, s[28:29]
	s_add_i32 m0, m0, 0x2000
	ds_read_b128 v[204:207], v173 offset:19456
	global_load_lds_dwordx4 v138, s[28:29]
	s_add_i32 m0, s46, 0x14000
	ds_read_b128 v[208:211], v173 offset:20480
	global_load_lds_dwordx4 v134, s[66:67]
	s_add_i32 m0, m0, 0x2000
	ds_read_b128 v[212:215], v173 offset:21504
	global_load_lds_dwordx4 v138, s[66:67]
	s_mov_b32 m0, s9
	ds_read_b128 v[216:219], v173 offset:22528
	global_load_lds_dwordx4 v132, s[30:31]
	s_mov_b32 m0, s51
	ds_read_b128 v[220:223], v173 offset:23552
	global_load_lds_dwordx4 v136, s[30:31]
	s_cmp_lg_i32 s70, 0
	s_cbranch_scc1 .Lpg8rx1
	s_waitcnt vmcnt(8)
; #define PG8_STAGE(bufoff, gbase, voff) do { _Pragma("unroll") for (int _i = 0; _i < 2; ++_i) \
;         __builtin_amdgcn_global_load_lds((const unsigned*)((const char*)(gbase) + (voff)[_i]), (PG8_LAS unsigned*)(lds + (bufoff) + ldsw + _i * 8192), 16, 0, 0); } while (0)
; #define PG8_LDA(dst, b, h) do { _Pragma("unroll") for (int m = 0; m < 4; ++m) _Pragma("unroll") for (int k = 0; k < 2; ++k) dst[m][k] = *(const PG8_LAS bf16x8*)(lds + PG8_SA(b, h) + aoff + m * 2048 + k * 1024); } while (0)
; #define PG8_LDB(dst, b, h) do { _Pragma("unroll") for (int n = 0; n < 2; ++n) _Pragma("unroll") for (int k = 0; k < 2; ++k) dst[n][k] = *(const PG8_LAS bf16x8*)(lds + PG8_SB(b, h) + boff + n * 2048 + k * 1024); } while (0)
; #define PG8_MMA(ai, bj, At, Bt) do { __builtin_amdgcn_s_setprio(1); _Pragma("unroll") for (int m = 0; m < 4; ++m) _Pragma("unroll") for (int n = 0; n < 2; ++n) _Pragma("unroll") for (int k = 0; k < 2; ++k) \
;         acc[ai][bj][m][n] = __builtin_amdgcn_mfma_f32_16x16x32_bf16(Bt[n][k], At[m][k], acc[ai][bj][m][n], 0, 0, 0); __builtin_amdgcn_s_setprio(0); } while (0)
; #define PG8_WAIT_V(n) asm volatile("s_waitcnt vmcnt(" #n ")" ::: "memory")
; #define PG8_WAIT_L(n) asm volatile("s_waitcnt lgkmcnt(" #n ")" ::: "memory")
; #define PG8_WAIT_V8_UNLESS(flag) asm volatile("s_cmp_lg_i32 %0, 0\n\ts_cbranch_scc1 .Lpg8rx%=\n\ts_waitcnt vmcnt(8)\n.Lpg8rx%=:" :: "s"(__builtin_amdgcn_readfirstlane(flag)) : "scc", "memory")
; #define PG8_BAR __builtin_amdgcn_s_barrier()
; #define PG8_SCHED __builtin_amdgcn_sched_barrier(0)
; template <class Epi, class Sched, bool ALIGN_EPI = false, bool SP2 = false>
; __device__ __forceinline__ void gemm_phase(PG8_LAS unsigned char* lds, const Gemm g, const Sched& S, const Epi& E) {
;     ...
;             PG8_WAIT_V8_UNLESS(rx); PG8_WAIT_L(0); PG8_BAR; PG8_MMA(1, 0, At, B0); PG8_MMA(1, 1, At, B1); PG8_BAR; PG8_SCHED;
;             PG8_STAGE(PG8_SA(0, 1), a2 + hstep, voffA); PG8_SCHED; PG8_LDB(B0, 1, 0); PG8_LDB(B1, 1, 1); PG8_SCHED; PG8_LDA(At, 1, 0);
;             PG8_WAIT_V(8); PG8_WAIT_L(0); PG8_BAR; PG8_MMA(0, 0, At, B0); PG8_MMA(0, 1, At, B1); PG8_BAR; PG8_SCHED;
.Lpg8rx1:
	s_waitcnt lgkmcnt(0)
	s_setprio 1
	s_barrier
	v_mfma_f32_16x16x32_bf16 v[60:63], v[144:147], v[178:181], v[60:63]
	v_mfma_f32_16x16x32_bf16 v[56:59], v[152:155], v[178:181], v[56:59]
	v_mfma_f32_16x16x32_bf16 v[44:47], v[144:147], v[186:189], v[44:47]
	v_mfma_f32_16x16x32_bf16 v[40:43], v[152:155], v[186:189], v[40:43]
	v_mfma_f32_16x16x32_bf16 v[28:31], v[144:147], v[208:211], v[28:31]
	v_mfma_f32_16x16x32_bf16 v[24:27], v[152:155], v[208:211], v[24:27]
	v_mfma_f32_16x16x32_bf16 v[12:15], v[144:147], v[216:219], v[12:15]
	v_mfma_f32_16x16x32_bf16 v[8:11], v[152:155], v[216:219], v[8:11]
	v_mfma_f32_16x16x32_bf16 v[60:63], v[148:151], v[182:185], v[60:63]
	v_mfma_f32_16x16x32_bf16 v[56:59], v[156:159], v[182:185], v[56:59]
	v_mfma_f32_16x16x32_bf16 v[44:47], v[148:151], v[204:207], v[44:47]
	v_mfma_f32_16x16x32_bf16 v[40:43], v[156:159], v[204:207], v[40:43]
	v_mfma_f32_16x16x32_bf16 v[28:31], v[148:151], v[212:215], v[28:31]
	v_mfma_f32_16x16x32_bf16 v[24:27], v[156:159], v[212:215], v[24:27]
	v_mfma_f32_16x16x32_bf16 v[12:15], v[148:151], v[220:223], v[12:15]
	v_mfma_f32_16x16x32_bf16 v[8:11], v[156:159], v[220:223], v[8:11]
	v_mfma_f32_16x16x32_bf16 v[52:55], v[160:163], v[178:181], v[52:55]
	v_mfma_f32_16x16x32_bf16 v[48:51], v[168:171], v[178:181], v[48:51]
	v_mfma_f32_16x16x32_bf16 v[36:39], v[160:163], v[186:189], v[36:39]
	v_mfma_f32_16x16x32_bf16 v[32:35], v[168:171], v[186:189], v[32:35]
	v_mfma_f32_16x16x32_bf16 v[20:23], v[160:163], v[208:211], v[20:23]
	v_mfma_f32_16x16x32_bf16 v[16:19], v[168:171], v[208:211], v[16:19]
	v_mfma_f32_16x16x32_bf16 v[4:7], v[160:163], v[216:219], v[4:7]
	v_mfma_f32_16x16x32_bf16 v[0:3], v[168:171], v[216:219], v[0:3]
	v_mfma_f32_16x16x32_bf16 v[52:55], v[164:167], v[182:185], v[52:55]
	v_mfma_f32_16x16x32_bf16 v[48:51], v[174:177], v[182:185], v[48:51]
	v_mfma_f32_16x16x32_bf16 v[36:39], v[164:167], v[204:207], v[36:39]
	v_mfma_f32_16x16x32_bf16 v[32:35], v[174:177], v[204:207], v[32:35]
	v_mfma_f32_16x16x32_bf16 v[20:23], v[164:167], v[212:215], v[20:23]
	v_mfma_f32_16x16x32_bf16 v[16:19], v[174:177], v[212:215], v[16:19]
	v_mfma_f32_16x16x32_bf16 v[4:7], v[164:167], v[220:223], v[4:7]
	v_mfma_f32_16x16x32_bf16 v[0:3], v[174:177], v[220:223], v[0:3]
	s_setprio 0
	s_barrier
	s_mov_b64 s[98:99], s[30:31]
	s_add_u32 s100, s30, 0x40000
	s_addc_u32 s101, s31, 0
	ds_read_b128 v[144:147], v128 offset:32768
	ds_read_b128 v[148:151], v128 offset:33792
	ds_read_b128 v[152:155], v128 offset:34816
	ds_read_b128 v[156:159], v128 offset:35840
	ds_read_b128 v[160:163], v128 offset:49152
	ds_read_b128 v[164:167], v128 offset:50176
	ds_read_b128 v[168:171], v128 offset:51200
	ds_read_b128 v[174:177], v128 offset:52224
	ds_read_b128 v[178:181], v173 offset:32768
	ds_read_b128 v[182:185], v173 offset:33792
	ds_read_b128 v[186:189], v173 offset:34816
	ds_read_b128 v[204:207], v173 offset:35840
	ds_read_b128 v[208:211], v173 offset:36864
	ds_read_b128 v[212:215], v173 offset:37888
	s_mov_b32 m0, s52
	ds_read_b128 v[216:219], v173 offset:38912
	global_load_lds_dwordx4 v132, s[100:101]
	s_mov_b32 m0, s53
	ds_read_b128 v[220:223], v173 offset:39936
	global_load_lds_dwordx4 v136, s[100:101]
	s_waitcnt vmcnt(8) lgkmcnt(0)
	s_setprio 1
	s_barrier
	v_mfma_f32_16x16x32_bf16 v[124:127], v[144:147], v[178:181], v[124:127]
	v_mfma_f32_16x16x32_bf16 v[120:123], v[152:155], v[178:181], v[120:123]
	v_mfma_f32_16x16x32_bf16 v[108:111], v[144:147], v[186:189], v[108:111]
	v_mfma_f32_16x16x32_bf16 v[104:107], v[152:155], v[186:189], v[104:107]
	v_mfma_f32_16x16x32_bf16 v[92:95], v[144:147], v[208:211], v[92:95]
	v_mfma_f32_16x16x32_bf16 v[88:91], v[152:155], v[208:211], v[88:91]
	v_mfma_f32_16x16x32_bf16 v[76:79], v[144:147], v[216:219], v[76:79]
	v_mfma_f32_16x16x32_bf16 v[72:75], v[152:155], v[216:219], v[72:75]
	v_mfma_f32_16x16x32_bf16 v[124:127], v[148:151], v[182:185], v[124:127]
	v_mfma_f32_16x16x32_bf16 v[120:123], v[156:159], v[182:185], v[120:123]
	v_mfma_f32_16x16x32_bf16 v[108:111], v[148:151], v[204:207], v[108:111]
	v_mfma_f32_16x16x32_bf16 v[104:107], v[156:159], v[204:207], v[104:107]
	v_mfma_f32_16x16x32_bf16 v[92:95], v[148:151], v[212:215], v[92:95]
	v_mfma_f32_16x16x32_bf16 v[88:91], v[156:159], v[212:215], v[88:91]
	v_mfma_f32_16x16x32_bf16 v[76:79], v[148:151], v[220:223], v[76:79]
	v_mfma_f32_16x16x32_bf16 v[72:75], v[156:159], v[220:223], v[72:75]
	v_mfma_f32_16x16x32_bf16 v[116:119], v[160:163], v[178:181], v[116:119]
	v_mfma_f32_16x16x32_bf16 v[112:115], v[168:171], v[178:181], v[112:115]
	v_mfma_f32_16x16x32_bf16 v[100:103], v[160:163], v[186:189], v[100:103]
	v_mfma_f32_16x16x32_bf16 v[96:99], v[168:171], v[186:189], v[96:99]
	v_mfma_f32_16x16x32_bf16 v[84:87], v[160:163], v[208:211], v[84:87]
	v_mfma_f32_16x16x32_bf16 v[80:83], v[168:171], v[208:211], v[80:83]
	v_mfma_f32_16x16x32_bf16 v[68:71], v[160:163], v[216:219], v[68:71]
	v_mfma_f32_16x16x32_bf16 v[64:67], v[168:171], v[216:219], v[64:67]
	v_mfma_f32_16x16x32_bf16 v[116:119], v[164:167], v[182:185], v[116:119]
	v_mfma_f32_16x16x32_bf16 v[112:115], v[174:177], v[182:185], v[112:115]
	v_mfma_f32_16x16x32_bf16 v[100:103], v[164:167], v[204:207], v[100:103]
	v_mfma_f32_16x16x32_bf16 v[96:99], v[174:177], v[204:207], v[96:99]
	v_mfma_f32_16x16x32_bf16 v[84:87], v[164:167], v[212:215], v[84:87]
	v_mfma_f32_16x16x32_bf16 v[80:83], v[174:177], v[212:215], v[80:83]
	v_mfma_f32_16x16x32_bf16 v[68:71], v[164:167], v[220:223], v[68:71]
	v_mfma_f32_16x16x32_bf16 v[64:67], v[174:177], v[220:223], v[64:67]
	s_setprio 0
	s_barrier
; #define PG8_STAGE(bufoff, gbase, voff) do { _Pragma("unroll") for (int _i = 0; _i < 2; ++_i) \
;         __builtin_amdgcn_global_load_lds((const unsigned*)((const char*)(gbase) + (voff)[_i]), (PG8_LAS unsigned*)(lds + (bufoff) + ldsw + _i * 8192), 16, 0, 0); } while (0)
; #define PG8_LDA(dst, b, h) do { _Pragma("unroll") for (int m = 0; m < 4; ++m) _Pragma("unroll") for (int k = 0; k < 2; ++k) dst[m][k] = *(const PG8_LAS bf16x8*)(lds + PG8_SA(b, h) + aoff + m * 2048 + k * 1024); } while (0)
; #define PG8_MMA(ai, bj, At, Bt) do { __builtin_amdgcn_s_setprio(1); _Pragma("unroll") for (int m = 0; m < 4; ++m) _Pragma("unroll") for (int n = 0; n < 2; ++n) _Pragma("unroll") for (int k = 0; k < 2; ++k) \
;         acc[ai][bj][m][n] = __builtin_amdgcn_mfma_f32_16x16x32_bf16(Bt[n][k], At[m][k], acc[ai][bj][m][n], 0, 0, 0); __builtin_amdgcn_s_setprio(0); } while (0)
; #define PG8_WAIT_V(n) asm volatile("s_waitcnt vmcnt(" #n ")" ::: "memory")
; #define PG8_WAIT_L(n) asm volatile("s_waitcnt lgkmcnt(" #n ")" ::: "memory")
; #define PG8_BAR __builtin_amdgcn_s_barrier()
; #define PG8_SCHED __builtin_amdgcn_sched_barrier(0)
; template <class Epi, class Sched, bool ALIGN_EPI = false, bool SP2 = false>
; __device__ __forceinline__ void gemm_phase(PG8_LAS unsigned char* lds, const Gemm g, const Sched& S, const Epi& E) {
;     ...
;             PG8_STAGE(PG8_SB(1, 0), b3, voffB); PG8_STAGE(PG8_SB(1, 1), b3 + hstep, voffB); PG8_STAGE(PG8_SA(1, 0), a3, voffA); PG8_SCHED; PG8_LDA(At, 1, 1);
;             PG8_WAIT_V(8); PG8_WAIT_L(0); PG8_BAR; PG8_MMA(1, 0, At, B0); PG8_MMA(1, 1, At, B1); PG8_BAR; PG8_SCHED;
;     ...
;         if constexpr (ALIGN_EPI) { if (wr == 0) PG8_BAR; }
	ds_read_b128 v[178:181], v173 offset:49152
	ds_read_b128 v[182:185], v173 offset:50176
	s_add_u32 s100, s28, 0x80
	s_addc_u32 s101, s29, 0
	s_add_u32 s28, s28, 0x40080
	s_addc_u32 s29, s29, 0
	s_add_u32 s98, s98, 0x80
	s_addc_u32 s99, s99, 0
	s_add_i32 m0, s46, 0x18000
	ds_read_b128 v[186:189], v173 offset:51200
	global_load_lds_dwordx4 v134, s[100:101]
	s_add_i32 m0, m0, 0x2000
	ds_read_b128 v[204:207], v173 offset:52224
	global_load_lds_dwordx4 v138, s[100:101]
	s_add_i32 m0, s46, 0x1c000
	ds_read_b128 v[208:211], v173 offset:53248
	global_load_lds_dwordx4 v134, s[28:29]
	s_add_i32 m0, m0, 0x2000
	ds_read_b128 v[212:215], v173 offset:54272
	global_load_lds_dwordx4 v138, s[28:29]
	s_mov_b32 m0, s54
	ds_read_b128 v[216:219], v173 offset:55296
	global_load_lds_dwordx4 v132, s[98:99]
	s_mov_b32 m0, s55
	ds_read_b128 v[220:223], v173 offset:56320
	global_load_lds_dwordx4 v136, s[98:99]
	s_waitcnt vmcnt(8) lgkmcnt(0)
	s_setprio 1
	s_barrier
	v_mfma_f32_16x16x32_bf16 v[60:63], v[144:147], v[178:181], v[60:63]
	v_mfma_f32_16x16x32_bf16 v[56:59], v[152:155], v[178:181], v[56:59]
	v_mfma_f32_16x16x32_bf16 v[44:47], v[144:147], v[186:189], v[44:47]
	v_mfma_f32_16x16x32_bf16 v[40:43], v[152:155], v[186:189], v[40:43]
	v_mfma_f32_16x16x32_bf16 v[28:31], v[144:147], v[208:211], v[28:31]
	v_mfma_f32_16x16x32_bf16 v[24:27], v[152:155], v[208:211], v[24:27]
	v_mfma_f32_16x16x32_bf16 v[12:15], v[144:147], v[216:219], v[12:15]
	v_mfma_f32_16x16x32_bf16 v[8:11], v[152:155], v[216:219], v[8:11]
	v_mfma_f32_16x16x32_bf16 v[60:63], v[148:151], v[182:185], v[60:63]
	v_mfma_f32_16x16x32_bf16 v[56:59], v[156:159], v[182:185], v[56:59]
	v_mfma_f32_16x16x32_bf16 v[44:47], v[148:151], v[204:207], v[44:47]
	v_mfma_f32_16x16x32_bf16 v[40:43], v[156:159], v[204:207], v[40:43]
	v_mfma_f32_16x16x32_bf16 v[28:31], v[148:151], v[212:215], v[28:31]
	v_mfma_f32_16x16x32_bf16 v[24:27], v[156:159], v[212:215], v[24:27]
	v_mfma_f32_16x16x32_bf16 v[12:15], v[148:151], v[220:223], v[12:15]
	v_mfma_f32_16x16x32_bf16 v[8:11], v[156:159], v[220:223], v[8:11]
	v_mfma_f32_16x16x32_bf16 v[52:55], v[160:163], v[178:181], v[52:55]
	v_mfma_f32_16x16x32_bf16 v[48:51], v[168:171], v[178:181], v[48:51]
	v_mfma_f32_16x16x32_bf16 v[36:39], v[160:163], v[186:189], v[36:39]
	v_mfma_f32_16x16x32_bf16 v[32:35], v[168:171], v[186:189], v[32:35]
	v_mfma_f32_16x16x32_bf16 v[20:23], v[160:163], v[208:211], v[20:23]
	v_mfma_f32_16x16x32_bf16 v[16:19], v[168:171], v[208:211], v[16:19]
	v_mfma_f32_16x16x32_bf16 v[4:7], v[160:163], v[216:219], v[4:7]
	v_mfma_f32_16x16x32_bf16 v[0:3], v[168:171], v[216:219], v[0:3]
	v_mfma_f32_16x16x32_bf16 v[52:55], v[164:167], v[182:185], v[52:55]
	v_mfma_f32_16x16x32_bf16 v[48:51], v[174:177], v[182:185], v[48:51]
	v_mfma_f32_16x16x32_bf16 v[36:39], v[164:167], v[204:207], v[36:39]
	v_mfma_f32_16x16x32_bf16 v[32:35], v[174:177], v[204:207], v[32:35]
	v_mfma_f32_16x16x32_bf16 v[20:23], v[164:167], v[212:215], v[20:23]
	v_mfma_f32_16x16x32_bf16 v[16:19], v[174:177], v[212:215], v[16:19]
	v_mfma_f32_16x16x32_bf16 v[4:7], v[164:167], v[220:223], v[4:7]
	v_mfma_f32_16x16x32_bf16 v[0:3], v[174:177], v[220:223], v[0:3]
	s_setprio 0
	s_barrier
	s_add_i32 s60, s60, 2
	s_add_u32 vcc_lo, vcc_lo, 0x100
	s_addc_u32 vcc_hi, vcc_hi, 0
	s_cmp_gt_u32 s60, 13
	s_cbranch_scc0 .LBB0_148
	s_mov_b32 s61, 0x10000
	s_mov_b32 s65, 0x14000
	s_mov_b32 s30, 0x18000
	s_mov_b32 s31, 0x1c000
	s_and_b64 vcc, exec, s[62:63]
	s_cbranch_vccz .LBB0_151
	s_barrier

; #define PG8_STAGE(bufoff, gbase, voff) do { _Pragma("unroll") for (int _i = 0; _i < 2; ++_i) \
;         __builtin_amdgcn_global_load_lds((const unsigned*)((const char*)(gbase) + (voff)[_i]), (PG8_LAS unsigned*)(lds + (bufoff) + ldsw + _i * 8192), 16, 0, 0); } while (0)
; #define PG8_LDA(dst, b, h) do { _Pragma("unroll") for (int m = 0; m < 4; ++m) _Pragma("unroll") for (int k = 0; k < 2; ++k) dst[m][k] = *(const PG8_LAS bf16x8*)(lds + PG8_SA(b, h) + aoff + m * 2048 + k * 1024); } while (0)
; #define PG8_LDB(dst, b, h) do { _Pragma("unroll") for (int n = 0; n < 2; ++n) _Pragma("unroll") for (int k = 0; k < 2; ++k) dst[n][k] = *(const PG8_LAS bf16x8*)(lds + PG8_SB(b, h) + boff + n * 2048 + k * 1024); } while (0)
; #define PG8_MMA(ai, bj, At, Bt) do { __builtin_amdgcn_s_setprio(1); _Pragma("unroll") for (int m = 0; m < 4; ++m) _Pragma("unroll") for (int n = 0; n < 2; ++n) _Pragma("unroll") for (int k = 0; k < 2; ++k) \
;         acc[ai][bj][m][n] = __builtin_amdgcn_mfma_f32_16x16x32_bf16(Bt[n][k], At[m][k], acc[ai][bj][m][n], 0, 0, 0); __builtin_amdgcn_s_setprio(0); } while (0)
; #define PG8_WAIT_L(n) asm volatile("s_waitcnt lgkmcnt(" #n ")" ::: "memory")
; #define PG8_BAR __builtin_amdgcn_s_barrier()
; template <class Epi, class Sched, bool ALIGN_EPI = false, bool SP2 = false>
; __device__ __forceinline__ void gemm_phase(PG8_LAS unsigned char* lds, const Gemm g, const Sched& S, const Epi& E) {
;     ...
;             const char* a1 = cA + (size_t)(t + 1) * kstep;
;             const char* a2 = last ? nA : cA + (size_t)(t + 2) * kstep; const char* b2 = last ? nB : cB + (size_t)(t + 2) * kstep;
;             const char* a3 = a2 + kstep; const char* b3 = b2 + kstep;
;             if (last && has_next) S.a_ready(nxt);
;             if constexpr (SP2) {
;             const int rx = (relax && t == 0) ? 1 : 0;
;             PG8_STAGE(PG8_SA(1, 1), a1 + hstep, voffA); PG8_SCHED; PG8_LDB(B0, 0, 0); PG8_LDB(B1, 0, 1); PG8_SCHED; PG8_LDA(At, 0, 0);
;             PG8_WAIT_V8_UNLESS(rx); PG8_WAIT_L(0); PG8_BAR; PG8_MMA(0, 0, At, B0); PG8_MMA(0, 1, At, B1); PG8_BAR; PG8_SCHED;
;             PG8_STAGE(PG8_SB(0, 0), b2, voffB); PG8_STAGE(PG8_SB(0, 1), b2 + hstep, voffB); PG8_STAGE(PG8_SA(0, 0), a2, voffA); PG8_SCHED; PG8_LDA(At, 0, 1);
;             PG8_WAIT_V8_UNLESS(rx); PG8_WAIT_L(0); PG8_BAR; PG8_MMA(1, 0, At, B0); PG8_MMA(1, 1, At, B1); PG8_BAR; PG8_SCHED;
.LBB0_514:
	s_add_u32 s28, s0, s62
	s_addc_u32 s29, s1, s63
	s_add_u32 s30, s28, 0x100
	s_addc_u32 s31, s29, 0
	s_add_u32 s98, s28, 0x40080
	s_addc_u32 s99, s29, 0
	s_add_u32 s59, s56, s62
	s_addc_u32 s65, s57, s63
	s_cmp_eq_u32 s62, 0
	s_cselect_b64 s[28:29], -1, 0
	s_and_b64 s[60:61], s[42:43], s[28:29]
	s_cmpk_eq_i32 s62, 0x700
	s_cselect_b32 s31, s19, s31
	s_cselect_b32 s30, s27, s30
	s_cselect_b32 s29, s17, s65
	s_cselect_b32 s28, s55, s59
	ds_read_b128 v[120:123], v116
	ds_read_b128 v[128:131], v116 offset:1024
	ds_read_b128 v[132:135], v116 offset:2048
	ds_read_b128 v[136:139], v116 offset:3072
	ds_read_b128 v[140:143], v116 offset:16384
	ds_read_b128 v[144:147], v116 offset:17408
	ds_read_b128 v[156:159], v116 offset:18432
	ds_read_b128 v[160:163], v116 offset:19456
	ds_read_b128 v[164:167], v248
	ds_read_b128 v[168:171], v248 offset:1024
	ds_read_b128 v[172:175], v248 offset:2048
	ds_read_b128 v[176:179], v248 offset:3072
	ds_read_b128 v[180:183], v248 offset:4096
	ds_read_b128 v[184:187], v248 offset:5120
	ds_read_b128 v[188:191], v248 offset:6144
	s_add_i32 m0, s41, 0xc000
	s_and_b32 s66, s60, 1
	global_load_lds_dwordx4 v204, s[98:99]
	s_add_i32 m0, s41, 0xe000
	ds_read_b128 v[214:217], v248 offset:7168
	global_load_lds_dwordx4 v206, s[98:99]
	s_cmp_lg_i32 s66, 0
	s_cbranch_scc1 .Lpg8rx2
	s_waitcnt vmcnt(8)
.Lpg8rx2:
	s_waitcnt lgkmcnt(0)
	s_setprio 1
	s_barrier
	v_mfma_f32_16x16x32_bf16 v[152:155], v[120:123], v[164:167], v[152:155]
	v_mfma_f32_16x16x32_bf16 v[148:151], v[132:135], v[164:167], v[148:151]
	v_mfma_f32_16x16x32_bf16 v[108:111], v[120:123], v[172:175], v[108:111]
	v_mfma_f32_16x16x32_bf16 v[104:107], v[132:135], v[172:175], v[104:107]
	v_mfma_f32_16x16x32_bf16 v[92:95], v[120:123], v[180:183], v[92:95]
	v_mfma_f32_16x16x32_bf16 v[88:91], v[132:135], v[180:183], v[88:91]
	v_mfma_f32_16x16x32_bf16 v[76:79], v[120:123], v[188:191], v[76:79]
	v_mfma_f32_16x16x32_bf16 v[72:75], v[132:135], v[188:191], v[72:75]
	v_mfma_f32_16x16x32_bf16 v[152:155], v[128:131], v[168:171], v[152:155]
	v_mfma_f32_16x16x32_bf16 v[148:151], v[136:139], v[168:171], v[148:151]
	v_mfma_f32_16x16x32_bf16 v[108:111], v[128:131], v[176:179], v[108:111]
	v_mfma_f32_16x16x32_bf16 v[104:107], v[136:139], v[176:179], v[104:107]
	v_mfma_f32_16x16x32_bf16 v[92:95], v[128:131], v[184:187], v[92:95]
	v_mfma_f32_16x16x32_bf16 v[88:91], v[136:139], v[184:187], v[88:91]
	v_mfma_f32_16x16x32_bf16 v[76:79], v[128:131], v[214:217], v[76:79]
	v_mfma_f32_16x16x32_bf16 v[72:75], v[136:139], v[214:217], v[72:75]
	v_mfma_f32_16x16x32_bf16 v[124:127], v[140:143], v[164:167], v[124:127]
	v_mfma_f32_16x16x32_bf16 v[112:115], v[156:159], v[164:167], v[112:115]
	v_mfma_f32_16x16x32_bf16 v[100:103], v[140:143], v[172:175], v[100:103]
	v_mfma_f32_16x16x32_bf16 v[96:99], v[156:159], v[172:175], v[96:99]
	v_mfma_f32_16x16x32_bf16 v[84:87], v[140:143], v[180:183], v[84:87]
	v_mfma_f32_16x16x32_bf16 v[80:83], v[156:159], v[180:183], v[80:83]
	v_mfma_f32_16x16x32_bf16 v[68:71], v[140:143], v[188:191], v[68:71]
	v_mfma_f32_16x16x32_bf16 v[64:67], v[156:159], v[188:191], v[64:67]
	v_mfma_f32_16x16x32_bf16 v[124:127], v[144:147], v[168:171], v[124:127]
	v_mfma_f32_16x16x32_bf16 v[112:115], v[160:163], v[168:171], v[112:115]
	v_mfma_f32_16x16x32_bf16 v[100:103], v[144:147], v[176:179], v[100:103]
	v_mfma_f32_16x16x32_bf16 v[96:99], v[160:163], v[176:179], v[96:99]
	v_mfma_f32_16x16x32_bf16 v[84:87], v[144:147], v[184:187], v[84:87]
	v_mfma_f32_16x16x32_bf16 v[80:83], v[160:163], v[184:187], v[80:83]
	v_mfma_f32_16x16x32_bf16 v[68:71], v[144:147], v[214:217], v[68:71]
	v_mfma_f32_16x16x32_bf16 v[64:67], v[160:163], v[214:217], v[64:67]
	s_setprio 0
	s_barrier
	ds_read_b128 v[164:167], v248 offset:16384
	ds_read_b128 v[168:171], v248 offset:17408
	s_add_u32 s60, s28, 0x40000
	s_addc_u32 s61, s29, 0
	s_add_i32 m0, s39, 0x10000
	ds_read_b128 v[172:175], v248 offset:18432
	global_load_lds_dwordx4 v194, s[28:29]
	s_add_i32 m0, m0, 0x2000
	ds_read_b128 v[176:179], v248 offset:19456
	global_load_lds_dwordx4 v208, s[28:29]
	s_add_i32 m0, s39, 0x14000
	ds_read_b128 v[180:183], v248 offset:20480
	global_load_lds_dwordx4 v194, s[60:61]
	s_add_i32 m0, m0, 0x2000
	ds_read_b128 v[184:187], v248 offset:21504
	global_load_lds_dwordx4 v208, s[60:61]
	s_mov_b32 m0, s41
	ds_read_b128 v[188:191], v248 offset:22528
	global_load_lds_dwordx4 v204, s[30:31]
	s_mov_b32 m0, s44
	ds_read_b128 v[214:217], v248 offset:23552
	global_load_lds_dwordx4 v206, s[30:31]
	s_cmp_lg_i32 s66, 0
	s_cbranch_scc1 .Lpg8rx3
	s_waitcnt vmcnt(8)
; #define PG8_STAGE(bufoff, gbase, voff) do { _Pragma("unroll") for (int _i = 0; _i < 2; ++_i) \
;         __builtin_amdgcn_global_load_lds((const unsigned*)((const char*)(gbase) + (voff)[_i]), (PG8_LAS unsigned*)(lds + (bufoff) + ldsw + _i * 8192), 16, 0, 0); } while (0)
; #define PG8_LDA(dst, b, h) do { _Pragma("unroll") for (int m = 0; m < 4; ++m) _Pragma("unroll") for (int k = 0; k < 2; ++k) dst[m][k] = *(const PG8_LAS bf16x8*)(lds + PG8_SA(b, h) + aoff + m * 2048 + k * 1024); } while (0)
; #define PG8_LDB(dst, b, h) do { _Pragma("unroll") for (int n = 0; n < 2; ++n) _Pragma("unroll") for (int k = 0; k < 2; ++k) dst[n][k] = *(const PG8_LAS bf16x8*)(lds + PG8_SB(b, h) + boff + n * 2048 + k * 1024); } while (0)
; #define PG8_MMA(ai, bj, At, Bt) do { __builtin_amdgcn_s_setprio(1); _Pragma("unroll") for (int m = 0; m < 4; ++m) _Pragma("unroll") for (int n = 0; n < 2; ++n) _Pragma("unroll") for (int k = 0; k < 2; ++k) \
;         acc[ai][bj][m][n] = __builtin_amdgcn_mfma_f32_16x16x32_bf16(Bt[n][k], At[m][k], acc[ai][bj][m][n], 0, 0, 0); __builtin_amdgcn_s_setprio(0); } while (0)
; #define PG8_WAIT_V(n) asm volatile("s_waitcnt vmcnt(" #n ")" ::: "memory")
; #define PG8_WAIT_L(n) asm volatile("s_waitcnt lgkmcnt(" #n ")" ::: "memory")
; #define PG8_WAIT_V8_UNLESS(flag) asm volatile("s_cmp_lg_i32 %0, 0\n\ts_cbranch_scc1 .Lpg8rx%=\n\ts_waitcnt vmcnt(8)\n.Lpg8rx%=:" :: "s"(__builtin_amdgcn_readfirstlane(flag)) : "scc", "memory")
; #define PG8_BAR __builtin_amdgcn_s_barrier()
; #define PG8_SCHED __builtin_amdgcn_sched_barrier(0)
; template <class Epi, class Sched, bool ALIGN_EPI = false, bool SP2 = false>
; __device__ __forceinline__ void gemm_phase(PG8_LAS unsigned char* lds, const Gemm g, const Sched& S, const Epi& E) {
;     ...
;             PG8_WAIT_V8_UNLESS(rx); PG8_WAIT_L(0); PG8_BAR; PG8_MMA(1, 0, At, B0); PG8_MMA(1, 1, At, B1); PG8_BAR; PG8_SCHED;
;             PG8_STAGE(PG8_SA(0, 1), a2 + hstep, voffA); PG8_SCHED; PG8_LDB(B0, 1, 0); PG8_LDB(B1, 1, 1); PG8_SCHED; PG8_LDA(At, 1, 0);
;             PG8_WAIT_V(8); PG8_WAIT_L(0); PG8_BAR; PG8_MMA(0, 0, At, B0); PG8_MMA(0, 1, At, B1); PG8_BAR; PG8_SCHED;
.Lpg8rx3:
	s_waitcnt lgkmcnt(0)
	s_setprio 1
	s_barrier
	v_mfma_f32_16x16x32_bf16 v[60:63], v[120:123], v[164:167], v[60:63]
	v_mfma_f32_16x16x32_bf16 v[56:59], v[132:135], v[164:167], v[56:59]
	v_mfma_f32_16x16x32_bf16 v[44:47], v[120:123], v[172:175], v[44:47]
	v_mfma_f32_16x16x32_bf16 v[40:43], v[132:135], v[172:175], v[40:43]
	v_mfma_f32_16x16x32_bf16 v[28:31], v[120:123], v[180:183], v[28:31]
	v_mfma_f32_16x16x32_bf16 v[24:27], v[132:135], v[180:183], v[24:27]
	v_mfma_f32_16x16x32_bf16 v[12:15], v[120:123], v[188:191], v[12:15]
	v_mfma_f32_16x16x32_bf16 v[8:11], v[132:135], v[188:191], v[8:11]
	v_mfma_f32_16x16x32_bf16 v[60:63], v[128:131], v[168:171], v[60:63]
	v_mfma_f32_16x16x32_bf16 v[56:59], v[136:139], v[168:171], v[56:59]
	v_mfma_f32_16x16x32_bf16 v[44:47], v[128:131], v[176:179], v[44:47]
	v_mfma_f32_16x16x32_bf16 v[40:43], v[136:139], v[176:179], v[40:43]
	v_mfma_f32_16x16x32_bf16 v[28:31], v[128:131], v[184:187], v[28:31]
	v_mfma_f32_16x16x32_bf16 v[24:27], v[136:139], v[184:187], v[24:27]
	v_mfma_f32_16x16x32_bf16 v[12:15], v[128:131], v[214:217], v[12:15]
	v_mfma_f32_16x16x32_bf16 v[8:11], v[136:139], v[214:217], v[8:11]
	v_mfma_f32_16x16x32_bf16 v[52:55], v[140:143], v[164:167], v[52:55]
	v_mfma_f32_16x16x32_bf16 v[48:51], v[156:159], v[164:167], v[48:51]
	v_mfma_f32_16x16x32_bf16 v[36:39], v[140:143], v[172:175], v[36:39]
	v_mfma_f32_16x16x32_bf16 v[32:35], v[156:159], v[172:175], v[32:35]
	v_mfma_f32_16x16x32_bf16 v[20:23], v[140:143], v[180:183], v[20:23]
	v_mfma_f32_16x16x32_bf16 v[16:19], v[156:159], v[180:183], v[16:19]
	v_mfma_f32_16x16x32_bf16 v[4:7], v[140:143], v[188:191], v[4:7]
	v_mfma_f32_16x16x32_bf16 v[0:3], v[156:159], v[188:191], v[0:3]
	v_mfma_f32_16x16x32_bf16 v[52:55], v[144:147], v[168:171], v[52:55]
	v_mfma_f32_16x16x32_bf16 v[48:51], v[160:163], v[168:171], v[48:51]
	v_mfma_f32_16x16x32_bf16 v[36:39], v[144:147], v[176:179], v[36:39]
	v_mfma_f32_16x16x32_bf16 v[32:35], v[160:163], v[176:179], v[32:35]
	v_mfma_f32_16x16x32_bf16 v[20:23], v[144:147], v[184:187], v[20:23]
	v_mfma_f32_16x16x32_bf16 v[16:19], v[160:163], v[184:187], v[16:19]
	v_mfma_f32_16x16x32_bf16 v[4:7], v[144:147], v[214:217], v[4:7]
	v_mfma_f32_16x16x32_bf16 v[0:3], v[160:163], v[214:217], v[0:3]
	s_setprio 0
	s_barrier
	s_mov_b64 s[98:99], s[30:31]
	s_add_u32 s100, s30, 0x40000
	s_addc_u32 s101, s31, 0
	ds_read_b128 v[120:123], v116 offset:32768
	ds_read_b128 v[128:131], v116 offset:33792
	ds_read_b128 v[132:135], v116 offset:34816
	ds_read_b128 v[136:139], v116 offset:35840
	ds_read_b128 v[140:143], v116 offset:49152
	ds_read_b128 v[144:147], v116 offset:50176
	ds_read_b128 v[156:159], v116 offset:51200
	ds_read_b128 v[160:163], v116 offset:52224
	ds_read_b128 v[164:167], v248 offset:32768
	ds_read_b128 v[168:171], v248 offset:33792
	ds_read_b128 v[172:175], v248 offset:34816
	ds_read_b128 v[176:179], v248 offset:35840
	ds_read_b128 v[180:183], v248 offset:36864
	ds_read_b128 v[184:187], v248 offset:37888
	s_mov_b32 m0, s46
	ds_read_b128 v[188:191], v248 offset:38912
	global_load_lds_dwordx4 v204, s[100:101]
	s_mov_b32 m0, s48
	ds_read_b128 v[214:217], v248 offset:39936
	global_load_lds_dwordx4 v206, s[100:101]
	s_waitcnt vmcnt(8) lgkmcnt(0)
	s_setprio 1
	s_barrier
	v_mfma_f32_16x16x32_bf16 v[152:155], v[120:123], v[164:167], v[152:155]
	v_mfma_f32_16x16x32_bf16 v[148:151], v[132:135], v[164:167], v[148:151]
	v_mfma_f32_16x16x32_bf16 v[108:111], v[120:123], v[172:175], v[108:111]
	v_mfma_f32_16x16x32_bf16 v[104:107], v[132:135], v[172:175], v[104:107]
	v_mfma_f32_16x16x32_bf16 v[92:95], v[120:123], v[180:183], v[92:95]
	v_mfma_f32_16x16x32_bf16 v[88:91], v[132:135], v[180:183], v[88:91]
	v_mfma_f32_16x16x32_bf16 v[76:79], v[120:123], v[188:191], v[76:79]
	v_mfma_f32_16x16x32_bf16 v[72:75], v[132:135], v[188:191], v[72:75]
	v_mfma_f32_16x16x32_bf16 v[152:155], v[128:131], v[168:171], v[152:155]
	v_mfma_f32_16x16x32_bf16 v[148:151], v[136:139], v[168:171], v[148:151]
	v_mfma_f32_16x16x32_bf16 v[108:111], v[128:131], v[176:179], v[108:111]
	v_mfma_f32_16x16x32_bf16 v[104:107], v[136:139], v[176:179], v[104:107]
	v_mfma_f32_16x16x32_bf16 v[92:95], v[128:131], v[184:187], v[92:95]
	v_mfma_f32_16x16x32_bf16 v[88:91], v[136:139], v[184:187], v[88:91]
	v_mfma_f32_16x16x32_bf16 v[76:79], v[128:131], v[214:217], v[76:79]
	v_mfma_f32_16x16x32_bf16 v[72:75], v[136:139], v[214:217], v[72:75]
	v_mfma_f32_16x16x32_bf16 v[124:127], v[140:143], v[164:167], v[124:127]
	v_mfma_f32_16x16x32_bf16 v[112:115], v[156:159], v[164:167], v[112:115]
	v_mfma_f32_16x16x32_bf16 v[100:103], v[140:143], v[172:175], v[100:103]
	v_mfma_f32_16x16x32_bf16 v[96:99], v[156:159], v[172:175], v[96:99]
	v_mfma_f32_16x16x32_bf16 v[84:87], v[140:143], v[180:183], v[84:87]
	v_mfma_f32_16x16x32_bf16 v[80:83], v[156:159], v[180:183], v[80:83]
	v_mfma_f32_16x16x32_bf16 v[68:71], v[140:143], v[188:191], v[68:71]
	v_mfma_f32_16x16x32_bf16 v[64:67], v[156:159], v[188:191], v[64:67]
	v_mfma_f32_16x16x32_bf16 v[124:127], v[144:147], v[168:171], v[124:127]
	v_mfma_f32_16x16x32_bf16 v[112:115], v[160:163], v[168:171], v[112:115]
	v_mfma_f32_16x16x32_bf16 v[100:103], v[144:147], v[176:179], v[100:103]
	v_mfma_f32_16x16x32_bf16 v[96:99], v[160:163], v[176:179], v[96:99]
	v_mfma_f32_16x16x32_bf16 v[84:87], v[144:147], v[184:187], v[84:87]
	v_mfma_f32_16x16x32_bf16 v[80:83], v[160:163], v[184:187], v[80:83]
	v_mfma_f32_16x16x32_bf16 v[68:71], v[144:147], v[214:217], v[68:71]
	v_mfma_f32_16x16x32_bf16 v[64:67], v[160:163], v[214:217], v[64:67]
	s_setprio 0
	s_barrier
; #define PG8_STAGE(bufoff, gbase, voff) do { _Pragma("unroll") for (int _i = 0; _i < 2; ++_i) \
;         __builtin_amdgcn_global_load_lds((const unsigned*)((const char*)(gbase) + (voff)[_i]), (PG8_LAS unsigned*)(lds + (bufoff) + ldsw + _i * 8192), 16, 0, 0); } while (0)
; #define PG8_LDA(dst, b, h) do { _Pragma("unroll") for (int m = 0; m < 4; ++m) _Pragma("unroll") for (int k = 0; k < 2; ++k) dst[m][k] = *(const PG8_LAS bf16x8*)(lds + PG8_SA(b, h) + aoff + m * 2048 + k * 1024); } while (0)
; #define PG8_MMA(ai, bj, At, Bt) do { __builtin_amdgcn_s_setprio(1); _Pragma("unroll") for (int m = 0; m < 4; ++m) _Pragma("unroll") for (int n = 0; n < 2; ++n) _Pragma("unroll") for (int k = 0; k < 2; ++k) \
;         acc[ai][bj][m][n] = __builtin_amdgcn_mfma_f32_16x16x32_bf16(Bt[n][k], At[m][k], acc[ai][bj][m][n], 0, 0, 0); __builtin_amdgcn_s_setprio(0); } while (0)
; #define PG8_WAIT_V(n) asm volatile("s_waitcnt vmcnt(" #n ")" ::: "memory")
; #define PG8_WAIT_L(n) asm volatile("s_waitcnt lgkmcnt(" #n ")" ::: "memory")
; #define PG8_BAR __builtin_amdgcn_s_barrier()
; #define PG8_SCHED __builtin_amdgcn_sched_barrier(0)
; template <class Epi, class Sched, bool ALIGN_EPI = false, bool SP2 = false>
; __device__ __forceinline__ void gemm_phase(PG8_LAS unsigned char* lds, const Gemm g, const Sched& S, const Epi& E) {
;     ...
;             PG8_STAGE(PG8_SB(1, 0), b3, voffB); PG8_STAGE(PG8_SB(1, 1), b3 + hstep, voffB); PG8_STAGE(PG8_SA(1, 0), a3, voffA); PG8_SCHED; PG8_LDA(At, 1, 1);
;             PG8_WAIT_V(8); PG8_WAIT_L(0); PG8_BAR; PG8_MMA(1, 0, At, B0); PG8_MMA(1, 1, At, B1); PG8_BAR; PG8_SCHED;
;     ...
;         if constexpr (ALIGN_EPI) { if (wr == 0) PG8_BAR; }
	ds_read_b128 v[164:167], v248 offset:49152
	ds_read_b128 v[168:171], v248 offset:50176
	s_add_u32 s100, s28, 0x80
	s_addc_u32 s101, s29, 0
	s_add_u32 s28, s28, 0x40080
	s_addc_u32 s29, s29, 0
	s_add_u32 s98, s98, 0x80
	s_addc_u32 s99, s99, 0
	s_add_i32 m0, s39, 0x18000
	ds_read_b128 v[172:175], v248 offset:51200
	global_load_lds_dwordx4 v194, s[100:101]
	s_add_i32 m0, m0, 0x2000
	ds_read_b128 v[176:179], v248 offset:52224
	global_load_lds_dwordx4 v208, s[100:101]
	s_add_i32 m0, s39, 0x1c000
	ds_read_b128 v[180:183], v248 offset:53248
	global_load_lds_dwordx4 v194, s[28:29]
	s_add_i32 m0, m0, 0x2000
	ds_read_b128 v[184:187], v248 offset:54272
	global_load_lds_dwordx4 v208, s[28:29]
	s_mov_b32 m0, s50
	ds_read_b128 v[188:191], v248 offset:55296
	global_load_lds_dwordx4 v204, s[98:99]
	s_mov_b32 m0, s51
	ds_read_b128 v[214:217], v248 offset:56320
	global_load_lds_dwordx4 v206, s[98:99]
	s_waitcnt vmcnt(8) lgkmcnt(0)
	s_setprio 1
	s_barrier
	v_mfma_f32_16x16x32_bf16 v[60:63], v[120:123], v[164:167], v[60:63]
	v_mfma_f32_16x16x32_bf16 v[56:59], v[132:135], v[164:167], v[56:59]
	v_mfma_f32_16x16x32_bf16 v[44:47], v[120:123], v[172:175], v[44:47]
	v_mfma_f32_16x16x32_bf16 v[40:43], v[132:135], v[172:175], v[40:43]
	v_mfma_f32_16x16x32_bf16 v[28:31], v[120:123], v[180:183], v[28:31]
	v_mfma_f32_16x16x32_bf16 v[24:27], v[132:135], v[180:183], v[24:27]
	v_mfma_f32_16x16x32_bf16 v[12:15], v[120:123], v[188:191], v[12:15]
	v_mfma_f32_16x16x32_bf16 v[8:11], v[132:135], v[188:191], v[8:11]
	v_mfma_f32_16x16x32_bf16 v[60:63], v[128:131], v[168:171], v[60:63]
	v_mfma_f32_16x16x32_bf16 v[56:59], v[136:139], v[168:171], v[56:59]
	v_mfma_f32_16x16x32_bf16 v[44:47], v[128:131], v[176:179], v[44:47]
	v_mfma_f32_16x16x32_bf16 v[40:43], v[136:139], v[176:179], v[40:43]
	v_mfma_f32_16x16x32_bf16 v[28:31], v[128:131], v[184:187], v[28:31]
	v_mfma_f32_16x16x32_bf16 v[24:27], v[136:139], v[184:187], v[24:27]
	v_mfma_f32_16x16x32_bf16 v[12:15], v[128:131], v[214:217], v[12:15]
	v_mfma_f32_16x16x32_bf16 v[8:11], v[136:139], v[214:217], v[8:11]
	v_mfma_f32_16x16x32_bf16 v[52:55], v[140:143], v[164:167], v[52:55]
	v_mfma_f32_16x16x32_bf16 v[48:51], v[156:159], v[164:167], v[48:51]
	v_mfma_f32_16x16x32_bf16 v[36:39], v[140:143], v[172:175], v[36:39]
	v_mfma_f32_16x16x32_bf16 v[32:35], v[156:159], v[172:175], v[32:35]
	v_mfma_f32_16x16x32_bf16 v[20:23], v[140:143], v[180:183], v[20:23]
	v_mfma_f32_16x16x32_bf16 v[16:19], v[156:159], v[180:183], v[16:19]
	v_mfma_f32_16x16x32_bf16 v[4:7], v[140:143], v[188:191], v[4:7]
	v_mfma_f32_16x16x32_bf16 v[0:3], v[156:159], v[188:191], v[0:3]
	v_mfma_f32_16x16x32_bf16 v[52:55], v[144:147], v[168:171], v[52:55]
	v_mfma_f32_16x16x32_bf16 v[48:51], v[160:163], v[168:171], v[48:51]
	v_mfma_f32_16x16x32_bf16 v[36:39], v[144:147], v[176:179], v[36:39]
	v_mfma_f32_16x16x32_bf16 v[32:35], v[160:163], v[176:179], v[32:35]
	v_mfma_f32_16x16x32_bf16 v[20:23], v[144:147], v[184:187], v[20:23]
	v_mfma_f32_16x16x32_bf16 v[16:19], v[160:163], v[184:187], v[16:19]
	v_mfma_f32_16x16x32_bf16 v[4:7], v[144:147], v[214:217], v[4:7]
	v_mfma_f32_16x16x32_bf16 v[0:3], v[160:163], v[214:217], v[0:3]
	s_setprio 0
	s_barrier
	s_add_i32 s58, s58, 2
	s_add_u32 s62, s62, 0x100
	s_addc_u32 s63, s63, 0
	s_cmp_gt_u32 s58, 13
	s_cbranch_scc0 .LBB0_514
	s_mov_b32 s59, 0x10000
	s_mov_b32 s65, 0x14000
	s_mov_b32 s30, 0x18000
	s_mov_b32 s31, 0x1c000
	s_and_b64 vcc, exec, s[14:15]
	s_cbranch_vccz .LBB0_517
	s_barrier

; #define PG8_STAGE(bufoff, gbase, voff) do { _Pragma("unroll") for (int _i = 0; _i < 2; ++_i) \
;         __builtin_amdgcn_global_load_lds((const unsigned*)((const char*)(gbase) + (voff)[_i]), (PG8_LAS unsigned*)(lds + (bufoff) + ldsw + _i * 8192), 16, 0, 0); } while (0)
; #define PG8_LDA(dst, b, h) do { _Pragma("unroll") for (int m = 0; m < 4; ++m) _Pragma("unroll") for (int k = 0; k < 2; ++k) dst[m][k] = *(const PG8_LAS bf16x8*)(lds + PG8_SA(b, h) + aoff + m * 2048 + k * 1024); } while (0)
; #define PG8_LDB(dst, b, h) do { _Pragma("unroll") for (int n = 0; n < 2; ++n) _Pragma("unroll") for (int k = 0; k < 2; ++k) dst[n][k] = *(const PG8_LAS bf16x8*)(lds + PG8_SB(b, h) + boff + n * 2048 + k * 1024); } while (0)
; #define PG8_MMA(ai, bj, At, Bt) do { __builtin_amdgcn_s_setprio(1); _Pragma("unroll") for (int m = 0; m < 4; ++m) _Pragma("unroll") for (int n = 0; n < 2; ++n) _Pragma("unroll") for (int k = 0; k < 2; ++k) \
;         acc[ai][bj][m][n] = __builtin_amdgcn_mfma_f32_16x16x32_bf16(Bt[n][k], At[m][k], acc[ai][bj][m][n], 0, 0, 0); __builtin_amdgcn_s_setprio(0); } while (0)
; #define PG8_WAIT_L(n) asm volatile("s_waitcnt lgkmcnt(" #n ")" ::: "memory")
; #define PG8_BAR __builtin_amdgcn_s_barrier()
; template <class Epi, class Sched, bool ALIGN_EPI = false, bool SP2 = false>
; __device__ __forceinline__ void gemm_phase(PG8_LAS unsigned char* lds, const Gemm g, const Sched& S, const Epi& E) {
;     ...
;             const char* a1 = cA + (size_t)(t + 1) * kstep;
;             const char* a2 = last ? nA : cA + (size_t)(t + 2) * kstep; const char* b2 = last ? nB : cB + (size_t)(t + 2) * kstep;
;             const char* a3 = a2 + kstep; const char* b3 = b2 + kstep;
;             if (last && has_next) S.a_ready(nxt);
;             if constexpr (SP2) {
;             const int rx = (relax && t == 0) ? 1 : 0;
;             PG8_STAGE(PG8_SA(1, 1), a1 + hstep, voffA); PG8_SCHED; PG8_LDB(B0, 0, 0); PG8_LDB(B1, 0, 1); PG8_SCHED; PG8_LDA(At, 0, 0);
;             PG8_WAIT_V8_UNLESS(rx); PG8_WAIT_L(0); PG8_BAR; PG8_MMA(0, 0, At, B0); PG8_MMA(0, 1, At, B1); PG8_BAR; PG8_SCHED;
;             PG8_STAGE(PG8_SB(0, 0), b2, voffB); PG8_STAGE(PG8_SB(0, 1), b2 + hstep, voffB); PG8_STAGE(PG8_SA(0, 0), a2, voffA); PG8_SCHED; PG8_LDA(At, 0, 1);
;             PG8_WAIT_V8_UNLESS(rx); PG8_WAIT_L(0); PG8_BAR; PG8_MMA(1, 0, At, B0); PG8_MMA(1, 1, At, B1); PG8_BAR; PG8_SCHED;
.LBB0_611:
	s_add_u32 s28, s24, s40
	s_addc_u32 s29, s25, s41
	s_add_u32 s30, s28, 0x100
	s_addc_u32 s31, s29, 0
	s_add_u32 s98, s28, 0x40080
	s_addc_u32 s99, s29, 0
	s_add_u32 s59, s56, s40
	s_addc_u32 s62, s57, s41
	s_cmp_eq_u32 s40, 0
	s_cselect_b64 s[28:29], -1, 0
	s_and_b64 s[60:61], s[26:27], s[28:29]
	s_cmpk_eq_i32 s40, 0x700
	s_cselect_b32 s31, s13, s31
	s_cselect_b32 s30, s54, s30
	s_cselect_b32 s29, s11, s62
	s_cselect_b32 s28, s55, s59
	ds_read_b128 v[132:135], v128
	ds_read_b128 v[136:139], v128 offset:1024
	ds_read_b128 v[140:143], v128 offset:2048
	ds_read_b128 v[144:147], v128 offset:3072
	ds_read_b128 v[148:151], v128 offset:16384
	ds_read_b128 v[164:167], v128 offset:17408
	ds_read_b128 v[168:171], v128 offset:18432
	ds_read_b128 v[172:175], v128 offset:19456
	ds_read_b128 v[176:179], v185
	ds_read_b128 v[186:189], v185 offset:1024
	ds_read_b128 v[204:207], v185 offset:2048
	ds_read_b128 v[208:211], v185 offset:3072
	ds_read_b128 v[212:215], v185 offset:4096
	ds_read_b128 v[216:219], v185 offset:5120
	ds_read_b128 v[220:223], v185 offset:6144
	s_add_i32 m0, s21, 0xc000
	s_and_b32 s63, s60, 1
	global_load_lds_dwordx4 v152, s[98:99]
	s_add_i32 m0, s21, 0xe000
	ds_read_b128 v[224:227], v185 offset:7168
	global_load_lds_dwordx4 v156, s[98:99]
	s_cmp_lg_i32 s63, 0
	s_cbranch_scc1 .Lpg8rx4
	s_waitcnt vmcnt(8)
.Lpg8rx4:
	s_waitcnt lgkmcnt(0)
	s_setprio 1
	s_barrier
	v_mfma_f32_16x16x32_bf16 v[124:127], v[132:135], v[176:179], v[124:127]
	v_mfma_f32_16x16x32_bf16 v[120:123], v[140:143], v[176:179], v[120:123]
	v_mfma_f32_16x16x32_bf16 v[108:111], v[132:135], v[204:207], v[108:111]
	v_mfma_f32_16x16x32_bf16 v[104:107], v[140:143], v[204:207], v[104:107]
	v_mfma_f32_16x16x32_bf16 v[92:95], v[132:135], v[212:215], v[92:95]
	v_mfma_f32_16x16x32_bf16 v[88:91], v[140:143], v[212:215], v[88:91]
	v_mfma_f32_16x16x32_bf16 v[76:79], v[132:135], v[220:223], v[76:79]
	v_mfma_f32_16x16x32_bf16 v[72:75], v[140:143], v[220:223], v[72:75]
	v_mfma_f32_16x16x32_bf16 v[124:127], v[136:139], v[186:189], v[124:127]
	v_mfma_f32_16x16x32_bf16 v[120:123], v[144:147], v[186:189], v[120:123]
	v_mfma_f32_16x16x32_bf16 v[108:111], v[136:139], v[208:211], v[108:111]
	v_mfma_f32_16x16x32_bf16 v[104:107], v[144:147], v[208:211], v[104:107]
	v_mfma_f32_16x16x32_bf16 v[92:95], v[136:139], v[216:219], v[92:95]
	v_mfma_f32_16x16x32_bf16 v[88:91], v[144:147], v[216:219], v[88:91]
	v_mfma_f32_16x16x32_bf16 v[76:79], v[136:139], v[224:227], v[76:79]
	v_mfma_f32_16x16x32_bf16 v[72:75], v[144:147], v[224:227], v[72:75]
	v_mfma_f32_16x16x32_bf16 v[116:119], v[148:151], v[176:179], v[116:119]
	v_mfma_f32_16x16x32_bf16 v[112:115], v[168:171], v[176:179], v[112:115]
	v_mfma_f32_16x16x32_bf16 v[100:103], v[148:151], v[204:207], v[100:103]
	v_mfma_f32_16x16x32_bf16 v[96:99], v[168:171], v[204:207], v[96:99]
	v_mfma_f32_16x16x32_bf16 v[84:87], v[148:151], v[212:215], v[84:87]
	v_mfma_f32_16x16x32_bf16 v[80:83], v[168:171], v[212:215], v[80:83]
	v_mfma_f32_16x16x32_bf16 v[68:71], v[148:151], v[220:223], v[68:71]
	v_mfma_f32_16x16x32_bf16 v[64:67], v[168:171], v[220:223], v[64:67]
	v_mfma_f32_16x16x32_bf16 v[116:119], v[164:167], v[186:189], v[116:119]
	v_mfma_f32_16x16x32_bf16 v[112:115], v[172:175], v[186:189], v[112:115]
	v_mfma_f32_16x16x32_bf16 v[100:103], v[164:167], v[208:211], v[100:103]
	v_mfma_f32_16x16x32_bf16 v[96:99], v[172:175], v[208:211], v[96:99]
	v_mfma_f32_16x16x32_bf16 v[84:87], v[164:167], v[216:219], v[84:87]
	v_mfma_f32_16x16x32_bf16 v[80:83], v[172:175], v[216:219], v[80:83]
	v_mfma_f32_16x16x32_bf16 v[68:71], v[164:167], v[224:227], v[68:71]
	v_mfma_f32_16x16x32_bf16 v[64:67], v[172:175], v[224:227], v[64:67]
	s_setprio 0
	s_barrier
	ds_read_b128 v[176:179], v185 offset:16384
	ds_read_b128 v[186:189], v185 offset:17408
	s_add_u32 s60, s28, 0x40000
	s_addc_u32 s61, s29, 0
	s_add_i32 m0, s38, 0x10000
	ds_read_b128 v[204:207], v185 offset:18432
	global_load_lds_dwordx4 v154, s[28:29]
	s_add_i32 m0, m0, 0x2000
	ds_read_b128 v[208:211], v185 offset:19456
	global_load_lds_dwordx4 v158, s[28:29]
	s_add_i32 m0, s38, 0x14000
	ds_read_b128 v[212:215], v185 offset:20480
	global_load_lds_dwordx4 v154, s[60:61]
	s_add_i32 m0, m0, 0x2000
	ds_read_b128 v[216:219], v185 offset:21504
	global_load_lds_dwordx4 v158, s[60:61]
	s_mov_b32 m0, s21
	ds_read_b128 v[220:223], v185 offset:22528
	global_load_lds_dwordx4 v152, s[30:31]
	s_mov_b32 m0, s23
	ds_read_b128 v[224:227], v185 offset:23552
	global_load_lds_dwordx4 v156, s[30:31]
	s_cmp_lg_i32 s63, 0
	s_cbranch_scc1 .Lpg8rx5
	s_waitcnt vmcnt(8)
; #define PG8_STAGE(bufoff, gbase, voff) do { _Pragma("unroll") for (int _i = 0; _i < 2; ++_i) \
;         __builtin_amdgcn_global_load_lds((const unsigned*)((const char*)(gbase) + (voff)[_i]), (PG8_LAS unsigned*)(lds + (bufoff) + ldsw + _i * 8192), 16, 0, 0); } while (0)
; #define PG8_LDA(dst, b, h) do { _Pragma("unroll") for (int m = 0; m < 4; ++m) _Pragma("unroll") for (int k = 0; k < 2; ++k) dst[m][k] = *(const PG8_LAS bf16x8*)(lds + PG8_SA(b, h) + aoff + m * 2048 + k * 1024); } while (0)
; #define PG8_LDB(dst, b, h) do { _Pragma("unroll") for (int n = 0; n < 2; ++n) _Pragma("unroll") for (int k = 0; k < 2; ++k) dst[n][k] = *(const PG8_LAS bf16x8*)(lds + PG8_SB(b, h) + boff + n * 2048 + k * 1024); } while (0)
; #define PG8_MMA(ai, bj, At, Bt) do { __builtin_amdgcn_s_setprio(1); _Pragma("unroll") for (int m = 0; m < 4; ++m) _Pragma("unroll") for (int n = 0; n < 2; ++n) _Pragma("unroll") for (int k = 0; k < 2; ++k) \
;         acc[ai][bj][m][n] = __builtin_amdgcn_mfma_f32_16x16x32_bf16(Bt[n][k], At[m][k], acc[ai][bj][m][n], 0, 0, 0); __builtin_amdgcn_s_setprio(0); } while (0)
; #define PG8_WAIT_V(n) asm volatile("s_waitcnt vmcnt(" #n ")" ::: "memory")
; #define PG8_WAIT_L(n) asm volatile("s_waitcnt lgkmcnt(" #n ")" ::: "memory")
; #define PG8_WAIT_V8_UNLESS(flag) asm volatile("s_cmp_lg_i32 %0, 0\n\ts_cbranch_scc1 .Lpg8rx%=\n\ts_waitcnt vmcnt(8)\n.Lpg8rx%=:" :: "s"(__builtin_amdgcn_readfirstlane(flag)) : "scc", "memory")
; #define PG8_BAR __builtin_amdgcn_s_barrier()
; #define PG8_SCHED __builtin_amdgcn_sched_barrier(0)
; template <class Epi, class Sched, bool ALIGN_EPI = false, bool SP2 = false>
; __device__ __forceinline__ void gemm_phase(PG8_LAS unsigned char* lds, const Gemm g, const Sched& S, const Epi& E) {
;     ...
;             PG8_WAIT_V8_UNLESS(rx); PG8_WAIT_L(0); PG8_BAR; PG8_MMA(1, 0, At, B0); PG8_MMA(1, 1, At, B1); PG8_BAR; PG8_SCHED;
;             PG8_STAGE(PG8_SA(0, 1), a2 + hstep, voffA); PG8_SCHED; PG8_LDB(B0, 1, 0); PG8_LDB(B1, 1, 1); PG8_SCHED; PG8_LDA(At, 1, 0);
;             PG8_WAIT_V(8); PG8_WAIT_L(0); PG8_BAR; PG8_MMA(0, 0, At, B0); PG8_MMA(0, 1, At, B1); PG8_BAR; PG8_SCHED;
.Lpg8rx5:
	s_waitcnt lgkmcnt(0)
	s_setprio 1
	s_barrier
	v_mfma_f32_16x16x32_bf16 v[60:63], v[132:135], v[176:179], v[60:63]
	v_mfma_f32_16x16x32_bf16 v[56:59], v[140:143], v[176:179], v[56:59]
	v_mfma_f32_16x16x32_bf16 v[44:47], v[132:135], v[204:207], v[44:47]
	v_mfma_f32_16x16x32_bf16 v[40:43], v[140:143], v[204:207], v[40:43]
	v_mfma_f32_16x16x32_bf16 v[28:31], v[132:135], v[212:215], v[28:31]
	v_mfma_f32_16x16x32_bf16 v[24:27], v[140:143], v[212:215], v[24:27]
	v_mfma_f32_16x16x32_bf16 v[12:15], v[132:135], v[220:223], v[12:15]
	v_mfma_f32_16x16x32_bf16 v[8:11], v[140:143], v[220:223], v[8:11]
	v_mfma_f32_16x16x32_bf16 v[60:63], v[136:139], v[186:189], v[60:63]
	v_mfma_f32_16x16x32_bf16 v[56:59], v[144:147], v[186:189], v[56:59]
	v_mfma_f32_16x16x32_bf16 v[44:47], v[136:139], v[208:211], v[44:47]
	v_mfma_f32_16x16x32_bf16 v[40:43], v[144:147], v[208:211], v[40:43]
	v_mfma_f32_16x16x32_bf16 v[28:31], v[136:139], v[216:219], v[28:31]
	v_mfma_f32_16x16x32_bf16 v[24:27], v[144:147], v[216:219], v[24:27]
	v_mfma_f32_16x16x32_bf16 v[12:15], v[136:139], v[224:227], v[12:15]
	v_mfma_f32_16x16x32_bf16 v[8:11], v[144:147], v[224:227], v[8:11]
	v_mfma_f32_16x16x32_bf16 v[52:55], v[148:151], v[176:179], v[52:55]
	v_mfma_f32_16x16x32_bf16 v[48:51], v[168:171], v[176:179], v[48:51]
	v_mfma_f32_16x16x32_bf16 v[36:39], v[148:151], v[204:207], v[36:39]
	v_mfma_f32_16x16x32_bf16 v[32:35], v[168:171], v[204:207], v[32:35]
	v_mfma_f32_16x16x32_bf16 v[20:23], v[148:151], v[212:215], v[20:23]
	v_mfma_f32_16x16x32_bf16 v[16:19], v[168:171], v[212:215], v[16:19]
	v_mfma_f32_16x16x32_bf16 v[4:7], v[148:151], v[220:223], v[4:7]
	v_mfma_f32_16x16x32_bf16 v[0:3], v[168:171], v[220:223], v[0:3]
	v_mfma_f32_16x16x32_bf16 v[52:55], v[164:167], v[186:189], v[52:55]
	v_mfma_f32_16x16x32_bf16 v[48:51], v[172:175], v[186:189], v[48:51]
	v_mfma_f32_16x16x32_bf16 v[36:39], v[164:167], v[208:211], v[36:39]
	v_mfma_f32_16x16x32_bf16 v[32:35], v[172:175], v[208:211], v[32:35]
	v_mfma_f32_16x16x32_bf16 v[20:23], v[164:167], v[216:219], v[20:23]
	v_mfma_f32_16x16x32_bf16 v[16:19], v[172:175], v[216:219], v[16:19]
	v_mfma_f32_16x16x32_bf16 v[4:7], v[164:167], v[224:227], v[4:7]
	v_mfma_f32_16x16x32_bf16 v[0:3], v[172:175], v[224:227], v[0:3]
	s_setprio 0
	s_barrier
	s_mov_b64 s[98:99], s[30:31]
	s_add_u32 s100, s30, 0x40000
	s_addc_u32 s101, s31, 0
	ds_read_b128 v[132:135], v128 offset:32768
	ds_read_b128 v[136:139], v128 offset:33792
	ds_read_b128 v[140:143], v128 offset:34816
	ds_read_b128 v[144:147], v128 offset:35840
	ds_read_b128 v[148:151], v128 offset:49152
	ds_read_b128 v[164:167], v128 offset:50176
	ds_read_b128 v[168:171], v128 offset:51200
	ds_read_b128 v[172:175], v128 offset:52224
	ds_read_b128 v[176:179], v185 offset:32768
	ds_read_b128 v[186:189], v185 offset:33792
	ds_read_b128 v[204:207], v185 offset:34816
	ds_read_b128 v[208:211], v185 offset:35840
	ds_read_b128 v[212:215], v185 offset:36864
	ds_read_b128 v[216:219], v185 offset:37888
	s_mov_b32 m0, s46
	ds_read_b128 v[220:223], v185 offset:38912
	global_load_lds_dwordx4 v152, s[100:101]
	s_mov_b32 m0, s48
	ds_read_b128 v[224:227], v185 offset:39936
	global_load_lds_dwordx4 v156, s[100:101]
	s_waitcnt vmcnt(8) lgkmcnt(0)
	s_setprio 1
	s_barrier
	v_mfma_f32_16x16x32_bf16 v[124:127], v[132:135], v[176:179], v[124:127]
	v_mfma_f32_16x16x32_bf16 v[120:123], v[140:143], v[176:179], v[120:123]
	v_mfma_f32_16x16x32_bf16 v[108:111], v[132:135], v[204:207], v[108:111]
	v_mfma_f32_16x16x32_bf16 v[104:107], v[140:143], v[204:207], v[104:107]
	v_mfma_f32_16x16x32_bf16 v[92:95], v[132:135], v[212:215], v[92:95]
	v_mfma_f32_16x16x32_bf16 v[88:91], v[140:143], v[212:215], v[88:91]
	v_mfma_f32_16x16x32_bf16 v[76:79], v[132:135], v[220:223], v[76:79]
	v_mfma_f32_16x16x32_bf16 v[72:75], v[140:143], v[220:223], v[72:75]
	v_mfma_f32_16x16x32_bf16 v[124:127], v[136:139], v[186:189], v[124:127]
	v_mfma_f32_16x16x32_bf16 v[120:123], v[144:147], v[186:189], v[120:123]
	v_mfma_f32_16x16x32_bf16 v[108:111], v[136:139], v[208:211], v[108:111]
	v_mfma_f32_16x16x32_bf16 v[104:107], v[144:147], v[208:211], v[104:107]
	v_mfma_f32_16x16x32_bf16 v[92:95], v[136:139], v[216:219], v[92:95]
	v_mfma_f32_16x16x32_bf16 v[88:91], v[144:147], v[216:219], v[88:91]
	v_mfma_f32_16x16x32_bf16 v[76:79], v[136:139], v[224:227], v[76:79]
	v_mfma_f32_16x16x32_bf16 v[72:75], v[144:147], v[224:227], v[72:75]
	v_mfma_f32_16x16x32_bf16 v[116:119], v[148:151], v[176:179], v[116:119]
	v_mfma_f32_16x16x32_bf16 v[112:115], v[168:171], v[176:179], v[112:115]
	v_mfma_f32_16x16x32_bf16 v[100:103], v[148:151], v[204:207], v[100:103]
	v_mfma_f32_16x16x32_bf16 v[96:99], v[168:171], v[204:207], v[96:99]
	v_mfma_f32_16x16x32_bf16 v[84:87], v[148:151], v[212:215], v[84:87]
	v_mfma_f32_16x16x32_bf16 v[80:83], v[168:171], v[212:215], v[80:83]
	v_mfma_f32_16x16x32_bf16 v[68:71], v[148:151], v[220:223], v[68:71]
	v_mfma_f32_16x16x32_bf16 v[64:67], v[168:171], v[220:223], v[64:67]
	v_mfma_f32_16x16x32_bf16 v[116:119], v[164:167], v[186:189], v[116:119]
	v_mfma_f32_16x16x32_bf16 v[112:115], v[172:175], v[186:189], v[112:115]
	v_mfma_f32_16x16x32_bf16 v[100:103], v[164:167], v[208:211], v[100:103]
	v_mfma_f32_16x16x32_bf16 v[96:99], v[172:175], v[208:211], v[96:99]
	v_mfma_f32_16x16x32_bf16 v[84:87], v[164:167], v[216:219], v[84:87]
	v_mfma_f32_16x16x32_bf16 v[80:83], v[172:175], v[216:219], v[80:83]
	v_mfma_f32_16x16x32_bf16 v[68:71], v[164:167], v[224:227], v[68:71]
	v_mfma_f32_16x16x32_bf16 v[64:67], v[172:175], v[224:227], v[64:67]
	s_setprio 0
	s_barrier
; #define PG8_STAGE(bufoff, gbase, voff) do { _Pragma("unroll") for (int _i = 0; _i < 2; ++_i) \
;         __builtin_amdgcn_global_load_lds((const unsigned*)((const char*)(gbase) + (voff)[_i]), (PG8_LAS unsigned*)(lds + (bufoff) + ldsw + _i * 8192), 16, 0, 0); } while (0)
; #define PG8_LDA(dst, b, h) do { _Pragma("unroll") for (int m = 0; m < 4; ++m) _Pragma("unroll") for (int k = 0; k < 2; ++k) dst[m][k] = *(const PG8_LAS bf16x8*)(lds + PG8_SA(b, h) + aoff + m * 2048 + k * 1024); } while (0)
; #define PG8_MMA(ai, bj, At, Bt) do { __builtin_amdgcn_s_setprio(1); _Pragma("unroll") for (int m = 0; m < 4; ++m) _Pragma("unroll") for (int n = 0; n < 2; ++n) _Pragma("unroll") for (int k = 0; k < 2; ++k) \
;         acc[ai][bj][m][n] = __builtin_amdgcn_mfma_f32_16x16x32_bf16(Bt[n][k], At[m][k], acc[ai][bj][m][n], 0, 0, 0); __builtin_amdgcn_s_setprio(0); } while (0)
; #define PG8_WAIT_V(n) asm volatile("s_waitcnt vmcnt(" #n ")" ::: "memory")
; #define PG8_WAIT_L(n) asm volatile("s_waitcnt lgkmcnt(" #n ")" ::: "memory")
; #define PG8_BAR __builtin_amdgcn_s_barrier()
; #define PG8_SCHED __builtin_amdgcn_sched_barrier(0)
; template <class Epi, class Sched, bool ALIGN_EPI = false, bool SP2 = false>
; __device__ __forceinline__ void gemm_phase(PG8_LAS unsigned char* lds, const Gemm g, const Sched& S, const Epi& E) {
;     ...
;             PG8_STAGE(PG8_SB(1, 0), b3, voffB); PG8_STAGE(PG8_SB(1, 1), b3 + hstep, voffB); PG8_STAGE(PG8_SA(1, 0), a3, voffA); PG8_SCHED; PG8_LDA(At, 1, 1);
;             PG8_WAIT_V(8); PG8_WAIT_L(0); PG8_BAR; PG8_MMA(1, 0, At, B0); PG8_MMA(1, 1, At, B1); PG8_BAR; PG8_SCHED;
;     ...
;         if constexpr (ALIGN_EPI) { if (wr == 0) PG8_BAR; }
	ds_read_b128 v[176:179], v185 offset:49152
	ds_read_b128 v[186:189], v185 offset:50176
	s_add_u32 s100, s28, 0x80
	s_addc_u32 s101, s29, 0
	s_add_u32 s28, s28, 0x40080
	s_addc_u32 s29, s29, 0
	s_add_u32 s98, s98, 0x80
	s_addc_u32 s99, s99, 0
	s_add_i32 m0, s38, 0x18000
	ds_read_b128 v[204:207], v185 offset:51200
	global_load_lds_dwordx4 v154, s[100:101]
	s_add_i32 m0, m0, 0x2000
	ds_read_b128 v[208:211], v185 offset:52224
	global_load_lds_dwordx4 v158, s[100:101]
	s_add_i32 m0, s38, 0x1c000
	ds_read_b128 v[212:215], v185 offset:53248
	global_load_lds_dwordx4 v154, s[28:29]
	s_add_i32 m0, m0, 0x2000
	ds_read_b128 v[216:219], v185 offset:54272
	global_load_lds_dwordx4 v158, s[28:29]
	s_mov_b32 m0, s50
	ds_read_b128 v[220:223], v185 offset:55296
	global_load_lds_dwordx4 v152, s[98:99]
	s_mov_b32 m0, s51
	ds_read_b128 v[224:227], v185 offset:56320
	global_load_lds_dwordx4 v156, s[98:99]
	s_waitcnt vmcnt(8) lgkmcnt(0)
	s_setprio 1
	s_barrier
	v_mfma_f32_16x16x32_bf16 v[60:63], v[132:135], v[176:179], v[60:63]
	v_mfma_f32_16x16x32_bf16 v[56:59], v[140:143], v[176:179], v[56:59]
	v_mfma_f32_16x16x32_bf16 v[44:47], v[132:135], v[204:207], v[44:47]
	v_mfma_f32_16x16x32_bf16 v[40:43], v[140:143], v[204:207], v[40:43]
	v_mfma_f32_16x16x32_bf16 v[28:31], v[132:135], v[212:215], v[28:31]
	v_mfma_f32_16x16x32_bf16 v[24:27], v[140:143], v[212:215], v[24:27]
	v_mfma_f32_16x16x32_bf16 v[12:15], v[132:135], v[220:223], v[12:15]
	v_mfma_f32_16x16x32_bf16 v[8:11], v[140:143], v[220:223], v[8:11]
	v_mfma_f32_16x16x32_bf16 v[60:63], v[136:139], v[186:189], v[60:63]
	v_mfma_f32_16x16x32_bf16 v[56:59], v[144:147], v[186:189], v[56:59]
	v_mfma_f32_16x16x32_bf16 v[44:47], v[136:139], v[208:211], v[44:47]
	v_mfma_f32_16x16x32_bf16 v[40:43], v[144:147], v[208:211], v[40:43]
	v_mfma_f32_16x16x32_bf16 v[28:31], v[136:139], v[216:219], v[28:31]
	v_mfma_f32_16x16x32_bf16 v[24:27], v[144:147], v[216:219], v[24:27]
	v_mfma_f32_16x16x32_bf16 v[12:15], v[136:139], v[224:227], v[12:15]
	v_mfma_f32_16x16x32_bf16 v[8:11], v[144:147], v[224:227], v[8:11]
	v_mfma_f32_16x16x32_bf16 v[52:55], v[148:151], v[176:179], v[52:55]
	v_mfma_f32_16x16x32_bf16 v[48:51], v[168:171], v[176:179], v[48:51]
	v_mfma_f32_16x16x32_bf16 v[36:39], v[148:151], v[204:207], v[36:39]
	v_mfma_f32_16x16x32_bf16 v[32:35], v[168:171], v[204:207], v[32:35]
	v_mfma_f32_16x16x32_bf16 v[20:23], v[148:151], v[212:215], v[20:23]
	v_mfma_f32_16x16x32_bf16 v[16:19], v[168:171], v[212:215], v[16:19]
	v_mfma_f32_16x16x32_bf16 v[4:7], v[148:151], v[220:223], v[4:7]
	v_mfma_f32_16x16x32_bf16 v[0:3], v[168:171], v[220:223], v[0:3]
	v_mfma_f32_16x16x32_bf16 v[52:55], v[164:167], v[186:189], v[52:55]
	v_mfma_f32_16x16x32_bf16 v[48:51], v[172:175], v[186:189], v[48:51]
	v_mfma_f32_16x16x32_bf16 v[36:39], v[164:167], v[208:211], v[36:39]
	v_mfma_f32_16x16x32_bf16 v[32:35], v[172:175], v[208:211], v[32:35]
	v_mfma_f32_16x16x32_bf16 v[20:23], v[164:167], v[216:219], v[20:23]
	v_mfma_f32_16x16x32_bf16 v[16:19], v[172:175], v[216:219], v[16:19]
	v_mfma_f32_16x16x32_bf16 v[4:7], v[164:167], v[224:227], v[4:7]
	v_mfma_f32_16x16x32_bf16 v[0:3], v[172:175], v[224:227], v[0:3]
	s_setprio 0
	s_barrier
	s_add_i32 s58, s58, 2
	s_add_u32 s40, s40, 0x100
	s_addc_u32 s41, s41, 0
	s_cmp_gt_u32 s58, 13
	s_cbranch_scc0 .LBB0_611
	s_mov_b32 s59, 0x10000
	s_mov_b32 s62, 0x14000
	s_mov_b32 s30, 0x18000
	s_mov_b32 s31, 0x1c000
	s_and_b64 vcc, exec, s[8:9]
	s_cbranch_vccz .LBB0_614
	s_barrier

; #define PG8_STAGE(bufoff, gbase, voff) do { _Pragma("unroll") for (int _i = 0; _i < 2; ++_i) \
;         __builtin_amdgcn_global_load_lds((const unsigned*)((const char*)(gbase) + (voff)[_i]), (PG8_LAS unsigned*)(lds + (bufoff) + ldsw + _i * 8192), 16, 0, 0); } while (0)
; #define PG8_LDA(dst, b, h) do { _Pragma("unroll") for (int m = 0; m < 4; ++m) _Pragma("unroll") for (int k = 0; k < 2; ++k) dst[m][k] = *(const PG8_LAS bf16x8*)(lds + PG8_SA(b, h) + aoff + m * 2048 + k * 1024); } while (0)
; #define PG8_LDB(dst, b, h) do { _Pragma("unroll") for (int n = 0; n < 2; ++n) _Pragma("unroll") for (int k = 0; k < 2; ++k) dst[n][k] = *(const PG8_LAS bf16x8*)(lds + PG8_SB(b, h) + boff + n * 2048 + k * 1024); } while (0)
; #define PG8_MMA(ai, bj, At, Bt) do { __builtin_amdgcn_s_setprio(1); _Pragma("unroll") for (int m = 0; m < 4; ++m) _Pragma("unroll") for (int n = 0; n < 2; ++n) _Pragma("unroll") for (int k = 0; k < 2; ++k) \
;         acc[ai][bj][m][n] = __builtin_amdgcn_mfma_f32_16x16x32_bf16(Bt[n][k], At[m][k], acc[ai][bj][m][n], 0, 0, 0); __builtin_amdgcn_s_setprio(0); } while (0)
; #define PG8_WAIT_L(n) asm volatile("s_waitcnt lgkmcnt(" #n ")" ::: "memory")
; #define PG8_BAR __builtin_amdgcn_s_barrier()
; template <class Epi, class Sched, bool ALIGN_EPI = false, bool SP2 = false>
; __device__ __forceinline__ void gemm_phase(PG8_LAS unsigned char* lds, const Gemm g, const Sched& S, const Epi& E) {
;     ...
;             const char* a1 = cA + (size_t)(t + 1) * kstep;
;             const char* a2 = last ? nA : cA + (size_t)(t + 2) * kstep; const char* b2 = last ? nB : cB + (size_t)(t + 2) * kstep;
;             const char* a3 = a2 + kstep; const char* b3 = b2 + kstep;
;             if (last && has_next) S.a_ready(nxt);
;             if constexpr (SP2) {
;             const int rx = (relax && t == 0) ? 1 : 0;
;             PG8_STAGE(PG8_SA(1, 1), a1 + hstep, voffA); PG8_SCHED; PG8_LDB(B0, 0, 0); PG8_LDB(B1, 0, 1); PG8_SCHED; PG8_LDA(At, 0, 0);
;             PG8_WAIT_V8_UNLESS(rx); PG8_WAIT_L(0); PG8_BAR; PG8_MMA(0, 0, At, B0); PG8_MMA(0, 1, At, B1); PG8_BAR; PG8_SCHED;
;             PG8_STAGE(PG8_SB(0, 0), b2, voffB); PG8_STAGE(PG8_SB(0, 1), b2 + hstep, voffB); PG8_STAGE(PG8_SA(0, 0), a2, voffA); PG8_SCHED; PG8_LDA(At, 0, 1);
;             PG8_WAIT_V8_UNLESS(rx); PG8_WAIT_L(0); PG8_BAR; PG8_MMA(1, 0, At, B0); PG8_MMA(1, 1, At, B1); PG8_BAR; PG8_SCHED;
.LBB0_965:
	s_add_u32 s28, s0, s40
	s_addc_u32 s29, s1, s41
	s_add_u32 s30, s28, 0x100
	s_addc_u32 s31, s29, 0
	s_add_u32 s98, s28, 0x100080
	s_addc_u32 s99, s29, 0
	s_add_u32 s57, s54, s40
	s_addc_u32 s60, s55, s41
	s_cmp_eq_u32 s40, 0
	s_cselect_b64 s[28:29], -1, 0
	s_and_b64 s[58:59], s[26:27], s[28:29]
	s_cmpk_eq_i32 s40, 0x1f00
	s_cselect_b32 s31, s15, s31
	s_cselect_b32 s30, s23, s30
	s_cselect_b32 s29, s13, s60
	s_cselect_b32 s28, s53, s57
	ds_read_b128 v[120:123], v116
	ds_read_b128 v[128:131], v116 offset:1024
	ds_read_b128 v[132:135], v116 offset:2048
	ds_read_b128 v[136:139], v116 offset:3072
	ds_read_b128 v[140:143], v116 offset:16384
	ds_read_b128 v[144:147], v116 offset:17408
	ds_read_b128 v[156:159], v116 offset:18432
	ds_read_b128 v[160:163], v116 offset:19456
	ds_read_b128 v[164:167], v248
	ds_read_b128 v[168:171], v248 offset:1024
	ds_read_b128 v[172:175], v248 offset:2048
	ds_read_b128 v[176:179], v248 offset:3072
	ds_read_b128 v[180:183], v248 offset:4096
	ds_read_b128 v[184:187], v248 offset:5120
	ds_read_b128 v[188:191], v248 offset:6144
	s_add_i32 m0, s25, 0xc000
	s_and_b32 s61, s58, 1
	global_load_lds_dwordx4 v204, s[98:99]
	s_add_i32 m0, s25, 0xe000
	ds_read_b128 v[214:217], v248 offset:7168
	global_load_lds_dwordx4 v206, s[98:99]
	s_cmp_lg_i32 s61, 0
	s_cbranch_scc1 .Lpg8rx6
	s_waitcnt vmcnt(8)
.Lpg8rx6:
	s_waitcnt lgkmcnt(0)
	s_setprio 1
	s_barrier
	v_mfma_f32_16x16x32_bf16 v[152:155], v[120:123], v[164:167], v[152:155]
	v_mfma_f32_16x16x32_bf16 v[148:151], v[132:135], v[164:167], v[148:151]
	v_mfma_f32_16x16x32_bf16 v[108:111], v[120:123], v[172:175], v[108:111]
	v_mfma_f32_16x16x32_bf16 v[104:107], v[132:135], v[172:175], v[104:107]
	v_mfma_f32_16x16x32_bf16 v[92:95], v[120:123], v[180:183], v[92:95]
	v_mfma_f32_16x16x32_bf16 v[88:91], v[132:135], v[180:183], v[88:91]
	v_mfma_f32_16x16x32_bf16 v[76:79], v[120:123], v[188:191], v[76:79]
	v_mfma_f32_16x16x32_bf16 v[72:75], v[132:135], v[188:191], v[72:75]
	v_mfma_f32_16x16x32_bf16 v[152:155], v[128:131], v[168:171], v[152:155]
	v_mfma_f32_16x16x32_bf16 v[148:151], v[136:139], v[168:171], v[148:151]
	v_mfma_f32_16x16x32_bf16 v[108:111], v[128:131], v[176:179], v[108:111]
	v_mfma_f32_16x16x32_bf16 v[104:107], v[136:139], v[176:179], v[104:107]
	v_mfma_f32_16x16x32_bf16 v[92:95], v[128:131], v[184:187], v[92:95]
	v_mfma_f32_16x16x32_bf16 v[88:91], v[136:139], v[184:187], v[88:91]
	v_mfma_f32_16x16x32_bf16 v[76:79], v[128:131], v[214:217], v[76:79]
	v_mfma_f32_16x16x32_bf16 v[72:75], v[136:139], v[214:217], v[72:75]
	v_mfma_f32_16x16x32_bf16 v[124:127], v[140:143], v[164:167], v[124:127]
	v_mfma_f32_16x16x32_bf16 v[112:115], v[156:159], v[164:167], v[112:115]
	v_mfma_f32_16x16x32_bf16 v[100:103], v[140:143], v[172:175], v[100:103]
	v_mfma_f32_16x16x32_bf16 v[96:99], v[156:159], v[172:175], v[96:99]
	v_mfma_f32_16x16x32_bf16 v[84:87], v[140:143], v[180:183], v[84:87]
	v_mfma_f32_16x16x32_bf16 v[80:83], v[156:159], v[180:183], v[80:83]
	v_mfma_f32_16x16x32_bf16 v[68:71], v[140:143], v[188:191], v[68:71]
	v_mfma_f32_16x16x32_bf16 v[64:67], v[156:159], v[188:191], v[64:67]
	v_mfma_f32_16x16x32_bf16 v[124:127], v[144:147], v[168:171], v[124:127]
	v_mfma_f32_16x16x32_bf16 v[112:115], v[160:163], v[168:171], v[112:115]
	v_mfma_f32_16x16x32_bf16 v[100:103], v[144:147], v[176:179], v[100:103]
	v_mfma_f32_16x16x32_bf16 v[96:99], v[160:163], v[176:179], v[96:99]
	v_mfma_f32_16x16x32_bf16 v[84:87], v[144:147], v[184:187], v[84:87]
	v_mfma_f32_16x16x32_bf16 v[80:83], v[160:163], v[184:187], v[80:83]
	v_mfma_f32_16x16x32_bf16 v[68:71], v[144:147], v[214:217], v[68:71]
	v_mfma_f32_16x16x32_bf16 v[64:67], v[160:163], v[214:217], v[64:67]
	s_setprio 0
	s_barrier
	ds_read_b128 v[164:167], v248 offset:16384
	ds_read_b128 v[168:171], v248 offset:17408
	s_add_u32 s58, s28, 0x100000
	s_addc_u32 s59, s29, 0
	s_add_i32 m0, s39, 0x10000
	ds_read_b128 v[172:175], v248 offset:18432
	global_load_lds_dwordx4 v194, s[28:29]
	s_add_i32 m0, m0, 0x2000
	ds_read_b128 v[176:179], v248 offset:19456
	global_load_lds_dwordx4 v208, s[28:29]
	s_add_i32 m0, s39, 0x14000
	ds_read_b128 v[180:183], v248 offset:20480
	global_load_lds_dwordx4 v194, s[58:59]
	s_add_i32 m0, m0, 0x2000
	ds_read_b128 v[184:187], v248 offset:21504
	global_load_lds_dwordx4 v208, s[58:59]
	s_mov_b32 m0, s25
	ds_read_b128 v[188:191], v248 offset:22528
	global_load_lds_dwordx4 v204, s[30:31]
	s_mov_b32 m0, s42
	ds_read_b128 v[214:217], v248 offset:23552
	global_load_lds_dwordx4 v206, s[30:31]
	s_cmp_lg_i32 s61, 0
	s_cbranch_scc1 .Lpg8rx7
	s_waitcnt vmcnt(8)
; #define PG8_STAGE(bufoff, gbase, voff) do { _Pragma("unroll") for (int _i = 0; _i < 2; ++_i) \
;         __builtin_amdgcn_global_load_lds((const unsigned*)((const char*)(gbase) + (voff)[_i]), (PG8_LAS unsigned*)(lds + (bufoff) + ldsw + _i * 8192), 16, 0, 0); } while (0)
; #define PG8_LDA(dst, b, h) do { _Pragma("unroll") for (int m = 0; m < 4; ++m) _Pragma("unroll") for (int k = 0; k < 2; ++k) dst[m][k] = *(const PG8_LAS bf16x8*)(lds + PG8_SA(b, h) + aoff + m * 2048 + k * 1024); } while (0)
; #define PG8_LDB(dst, b, h) do { _Pragma("unroll") for (int n = 0; n < 2; ++n) _Pragma("unroll") for (int k = 0; k < 2; ++k) dst[n][k] = *(const PG8_LAS bf16x8*)(lds + PG8_SB(b, h) + boff + n * 2048 + k * 1024); } while (0)
; #define PG8_MMA(ai, bj, At, Bt) do { __builtin_amdgcn_s_setprio(1); _Pragma("unroll") for (int m = 0; m < 4; ++m) _Pragma("unroll") for (int n = 0; n < 2; ++n) _Pragma("unroll") for (int k = 0; k < 2; ++k) \
;         acc[ai][bj][m][n] = __builtin_amdgcn_mfma_f32_16x16x32_bf16(Bt[n][k], At[m][k], acc[ai][bj][m][n], 0, 0, 0); __builtin_amdgcn_s_setprio(0); } while (0)
; #define PG8_WAIT_V(n) asm volatile("s_waitcnt vmcnt(" #n ")" ::: "memory")
; #define PG8_WAIT_L(n) asm volatile("s_waitcnt lgkmcnt(" #n ")" ::: "memory")
; #define PG8_WAIT_V8_UNLESS(flag) asm volatile("s_cmp_lg_i32 %0, 0\n\ts_cbranch_scc1 .Lpg8rx%=\n\ts_waitcnt vmcnt(8)\n.Lpg8rx%=:" :: "s"(__builtin_amdgcn_readfirstlane(flag)) : "scc", "memory")
; #define PG8_BAR __builtin_amdgcn_s_barrier()
; #define PG8_SCHED __builtin_amdgcn_sched_barrier(0)
; template <class Epi, class Sched, bool ALIGN_EPI = false, bool SP2 = false>
; __device__ __forceinline__ void gemm_phase(PG8_LAS unsigned char* lds, const Gemm g, const Sched& S, const Epi& E) {
;     ...
;             PG8_WAIT_V8_UNLESS(rx); PG8_WAIT_L(0); PG8_BAR; PG8_MMA(1, 0, At, B0); PG8_MMA(1, 1, At, B1); PG8_BAR; PG8_SCHED;
;             PG8_STAGE(PG8_SA(0, 1), a2 + hstep, voffA); PG8_SCHED; PG8_LDB(B0, 1, 0); PG8_LDB(B1, 1, 1); PG8_SCHED; PG8_LDA(At, 1, 0);
;             PG8_WAIT_V(8); PG8_WAIT_L(0); PG8_BAR; PG8_MMA(0, 0, At, B0); PG8_MMA(0, 1, At, B1); PG8_BAR; PG8_SCHED;
.Lpg8rx7:
	s_waitcnt lgkmcnt(0)
	s_setprio 1
	s_barrier
	v_mfma_f32_16x16x32_bf16 v[60:63], v[120:123], v[164:167], v[60:63]
	v_mfma_f32_16x16x32_bf16 v[56:59], v[132:135], v[164:167], v[56:59]
	v_mfma_f32_16x16x32_bf16 v[44:47], v[120:123], v[172:175], v[44:47]
	v_mfma_f32_16x16x32_bf16 v[40:43], v[132:135], v[172:175], v[40:43]
	v_mfma_f32_16x16x32_bf16 v[28:31], v[120:123], v[180:183], v[28:31]
	v_mfma_f32_16x16x32_bf16 v[24:27], v[132:135], v[180:183], v[24:27]
	v_mfma_f32_16x16x32_bf16 v[12:15], v[120:123], v[188:191], v[12:15]
	v_mfma_f32_16x16x32_bf16 v[8:11], v[132:135], v[188:191], v[8:11]
	v_mfma_f32_16x16x32_bf16 v[60:63], v[128:131], v[168:171], v[60:63]
	v_mfma_f32_16x16x32_bf16 v[56:59], v[136:139], v[168:171], v[56:59]
	v_mfma_f32_16x16x32_bf16 v[44:47], v[128:131], v[176:179], v[44:47]
	v_mfma_f32_16x16x32_bf16 v[40:43], v[136:139], v[176:179], v[40:43]
	v_mfma_f32_16x16x32_bf16 v[28:31], v[128:131], v[184:187], v[28:31]
	v_mfma_f32_16x16x32_bf16 v[24:27], v[136:139], v[184:187], v[24:27]
	v_mfma_f32_16x16x32_bf16 v[12:15], v[128:131], v[214:217], v[12:15]
	v_mfma_f32_16x16x32_bf16 v[8:11], v[136:139], v[214:217], v[8:11]
	v_mfma_f32_16x16x32_bf16 v[52:55], v[140:143], v[164:167], v[52:55]
	v_mfma_f32_16x16x32_bf16 v[48:51], v[156:159], v[164:167], v[48:51]
	v_mfma_f32_16x16x32_bf16 v[36:39], v[140:143], v[172:175], v[36:39]
	v_mfma_f32_16x16x32_bf16 v[32:35], v[156:159], v[172:175], v[32:35]
	v_mfma_f32_16x16x32_bf16 v[20:23], v[140:143], v[180:183], v[20:23]
	v_mfma_f32_16x16x32_bf16 v[16:19], v[156:159], v[180:183], v[16:19]
	v_mfma_f32_16x16x32_bf16 v[4:7], v[140:143], v[188:191], v[4:7]
	v_mfma_f32_16x16x32_bf16 v[0:3], v[156:159], v[188:191], v[0:3]
	v_mfma_f32_16x16x32_bf16 v[52:55], v[144:147], v[168:171], v[52:55]
	v_mfma_f32_16x16x32_bf16 v[48:51], v[160:163], v[168:171], v[48:51]
	v_mfma_f32_16x16x32_bf16 v[36:39], v[144:147], v[176:179], v[36:39]
	v_mfma_f32_16x16x32_bf16 v[32:35], v[160:163], v[176:179], v[32:35]
	v_mfma_f32_16x16x32_bf16 v[20:23], v[144:147], v[184:187], v[20:23]
	v_mfma_f32_16x16x32_bf16 v[16:19], v[160:163], v[184:187], v[16:19]
	v_mfma_f32_16x16x32_bf16 v[4:7], v[144:147], v[214:217], v[4:7]
	v_mfma_f32_16x16x32_bf16 v[0:3], v[160:163], v[214:217], v[0:3]
	s_setprio 0
	s_barrier
	s_mov_b64 s[98:99], s[30:31]
	s_add_u32 s100, s30, 0x100000
	s_addc_u32 s101, s31, 0
	ds_read_b128 v[120:123], v116 offset:32768
	ds_read_b128 v[128:131], v116 offset:33792
	ds_read_b128 v[132:135], v116 offset:34816
	ds_read_b128 v[136:139], v116 offset:35840
	ds_read_b128 v[140:143], v116 offset:49152
	ds_read_b128 v[144:147], v116 offset:50176
	ds_read_b128 v[156:159], v116 offset:51200
	ds_read_b128 v[160:163], v116 offset:52224
	ds_read_b128 v[164:167], v248 offset:32768
	ds_read_b128 v[168:171], v248 offset:33792
	ds_read_b128 v[172:175], v248 offset:34816
	ds_read_b128 v[176:179], v248 offset:35840
	ds_read_b128 v[180:183], v248 offset:36864
	ds_read_b128 v[184:187], v248 offset:37888
	s_mov_b32 m0, s43
	ds_read_b128 v[188:191], v248 offset:38912
	global_load_lds_dwordx4 v204, s[100:101]
	s_mov_b32 m0, s44
	ds_read_b128 v[214:217], v248 offset:39936
	global_load_lds_dwordx4 v206, s[100:101]
	s_waitcnt vmcnt(8) lgkmcnt(0)
	s_setprio 1
	s_barrier
	v_mfma_f32_16x16x32_bf16 v[152:155], v[120:123], v[164:167], v[152:155]
	v_mfma_f32_16x16x32_bf16 v[148:151], v[132:135], v[164:167], v[148:151]
	v_mfma_f32_16x16x32_bf16 v[108:111], v[120:123], v[172:175], v[108:111]
	v_mfma_f32_16x16x32_bf16 v[104:107], v[132:135], v[172:175], v[104:107]
	v_mfma_f32_16x16x32_bf16 v[92:95], v[120:123], v[180:183], v[92:95]
	v_mfma_f32_16x16x32_bf16 v[88:91], v[132:135], v[180:183], v[88:91]
	v_mfma_f32_16x16x32_bf16 v[76:79], v[120:123], v[188:191], v[76:79]
	v_mfma_f32_16x16x32_bf16 v[72:75], v[132:135], v[188:191], v[72:75]
	v_mfma_f32_16x16x32_bf16 v[152:155], v[128:131], v[168:171], v[152:155]
	v_mfma_f32_16x16x32_bf16 v[148:151], v[136:139], v[168:171], v[148:151]
	v_mfma_f32_16x16x32_bf16 v[108:111], v[128:131], v[176:179], v[108:111]
	v_mfma_f32_16x16x32_bf16 v[104:107], v[136:139], v[176:179], v[104:107]
	v_mfma_f32_16x16x32_bf16 v[92:95], v[128:131], v[184:187], v[92:95]
	v_mfma_f32_16x16x32_bf16 v[88:91], v[136:139], v[184:187], v[88:91]
	v_mfma_f32_16x16x32_bf16 v[76:79], v[128:131], v[214:217], v[76:79]
	v_mfma_f32_16x16x32_bf16 v[72:75], v[136:139], v[214:217], v[72:75]
	v_mfma_f32_16x16x32_bf16 v[124:127], v[140:143], v[164:167], v[124:127]
	v_mfma_f32_16x16x32_bf16 v[112:115], v[156:159], v[164:167], v[112:115]
	v_mfma_f32_16x16x32_bf16 v[100:103], v[140:143], v[172:175], v[100:103]
	v_mfma_f32_16x16x32_bf16 v[96:99], v[156:159], v[172:175], v[96:99]
	v_mfma_f32_16x16x32_bf16 v[84:87], v[140:143], v[180:183], v[84:87]
	v_mfma_f32_16x16x32_bf16 v[80:83], v[156:159], v[180:183], v[80:83]
	v_mfma_f32_16x16x32_bf16 v[68:71], v[140:143], v[188:191], v[68:71]
	v_mfma_f32_16x16x32_bf16 v[64:67], v[156:159], v[188:191], v[64:67]
	v_mfma_f32_16x16x32_bf16 v[124:127], v[144:147], v[168:171], v[124:127]
	v_mfma_f32_16x16x32_bf16 v[112:115], v[160:163], v[168:171], v[112:115]
	v_mfma_f32_16x16x32_bf16 v[100:103], v[144:147], v[176:179], v[100:103]
	v_mfma_f32_16x16x32_bf16 v[96:99], v[160:163], v[176:179], v[96:99]
	v_mfma_f32_16x16x32_bf16 v[84:87], v[144:147], v[184:187], v[84:87]
	v_mfma_f32_16x16x32_bf16 v[80:83], v[160:163], v[184:187], v[80:83]
	v_mfma_f32_16x16x32_bf16 v[68:71], v[144:147], v[214:217], v[68:71]
	v_mfma_f32_16x16x32_bf16 v[64:67], v[160:163], v[214:217], v[64:67]
	s_setprio 0
	s_barrier
; #define PG8_STAGE(bufoff, gbase, voff) do { _Pragma("unroll") for (int _i = 0; _i < 2; ++_i) \
;         __builtin_amdgcn_global_load_lds((const unsigned*)((const char*)(gbase) + (voff)[_i]), (PG8_LAS unsigned*)(lds + (bufoff) + ldsw + _i * 8192), 16, 0, 0); } while (0)
; #define PG8_LDA(dst, b, h) do { _Pragma("unroll") for (int m = 0; m < 4; ++m) _Pragma("unroll") for (int k = 0; k < 2; ++k) dst[m][k] = *(const PG8_LAS bf16x8*)(lds + PG8_SA(b, h) + aoff + m * 2048 + k * 1024); } while (0)
; #define PG8_MMA(ai, bj, At, Bt) do { __builtin_amdgcn_s_setprio(1); _Pragma("unroll") for (int m = 0; m < 4; ++m) _Pragma("unroll") for (int n = 0; n < 2; ++n) _Pragma("unroll") for (int k = 0; k < 2; ++k) \
;         acc[ai][bj][m][n] = __builtin_amdgcn_mfma_f32_16x16x32_bf16(Bt[n][k], At[m][k], acc[ai][bj][m][n], 0, 0, 0); __builtin_amdgcn_s_setprio(0); } while (0)
; #define PG8_WAIT_V(n) asm volatile("s_waitcnt vmcnt(" #n ")" ::: "memory")
; #define PG8_WAIT_L(n) asm volatile("s_waitcnt lgkmcnt(" #n ")" ::: "memory")
; #define PG8_BAR __builtin_amdgcn_s_barrier()
; #define PG8_SCHED __builtin_amdgcn_sched_barrier(0)
; template <class Epi, class Sched, bool ALIGN_EPI = false, bool SP2 = false>
; __device__ __forceinline__ void gemm_phase(PG8_LAS unsigned char* lds, const Gemm g, const Sched& S, const Epi& E) {
;     ...
;             PG8_STAGE(PG8_SB(1, 0), b3, voffB); PG8_STAGE(PG8_SB(1, 1), b3 + hstep, voffB); PG8_STAGE(PG8_SA(1, 0), a3, voffA); PG8_SCHED; PG8_LDA(At, 1, 1);
;             PG8_WAIT_V(8); PG8_WAIT_L(0); PG8_BAR; PG8_MMA(1, 0, At, B0); PG8_MMA(1, 1, At, B1); PG8_BAR; PG8_SCHED;
;     ...
;         if constexpr (ALIGN_EPI) { if (wr == 0) PG8_BAR; }
	ds_read_b128 v[164:167], v248 offset:49152
	ds_read_b128 v[168:171], v248 offset:50176
	s_add_u32 s100, s28, 0x80
	s_addc_u32 s101, s29, 0
	s_add_u32 s28, s28, 0x100080
	s_addc_u32 s29, s29, 0
	s_add_u32 s98, s98, 0x80
	s_addc_u32 s99, s99, 0
	s_add_i32 m0, s39, 0x18000
	ds_read_b128 v[172:175], v248 offset:51200
	global_load_lds_dwordx4 v194, s[100:101]
	s_add_i32 m0, m0, 0x2000
	ds_read_b128 v[176:179], v248 offset:52224
	global_load_lds_dwordx4 v208, s[100:101]
	s_add_i32 m0, s39, 0x1c000
	ds_read_b128 v[180:183], v248 offset:53248
	global_load_lds_dwordx4 v194, s[28:29]
	s_add_i32 m0, m0, 0x2000
	ds_read_b128 v[184:187], v248 offset:54272
	global_load_lds_dwordx4 v208, s[28:29]
	s_mov_b32 m0, s46
	ds_read_b128 v[188:191], v248 offset:55296
	global_load_lds_dwordx4 v204, s[98:99]
	s_mov_b32 m0, s48
	ds_read_b128 v[214:217], v248 offset:56320
	global_load_lds_dwordx4 v206, s[98:99]
	s_waitcnt vmcnt(8) lgkmcnt(0)
	s_setprio 1
	s_barrier
	v_mfma_f32_16x16x32_bf16 v[60:63], v[120:123], v[164:167], v[60:63]
	v_mfma_f32_16x16x32_bf16 v[56:59], v[132:135], v[164:167], v[56:59]
	v_mfma_f32_16x16x32_bf16 v[44:47], v[120:123], v[172:175], v[44:47]
	v_mfma_f32_16x16x32_bf16 v[40:43], v[132:135], v[172:175], v[40:43]
	v_mfma_f32_16x16x32_bf16 v[28:31], v[120:123], v[180:183], v[28:31]
	v_mfma_f32_16x16x32_bf16 v[24:27], v[132:135], v[180:183], v[24:27]
	v_mfma_f32_16x16x32_bf16 v[12:15], v[120:123], v[188:191], v[12:15]
	v_mfma_f32_16x16x32_bf16 v[8:11], v[132:135], v[188:191], v[8:11]
	v_mfma_f32_16x16x32_bf16 v[60:63], v[128:131], v[168:171], v[60:63]
	v_mfma_f32_16x16x32_bf16 v[56:59], v[136:139], v[168:171], v[56:59]
	v_mfma_f32_16x16x32_bf16 v[44:47], v[128:131], v[176:179], v[44:47]
	v_mfma_f32_16x16x32_bf16 v[40:43], v[136:139], v[176:179], v[40:43]
	v_mfma_f32_16x16x32_bf16 v[28:31], v[128:131], v[184:187], v[28:31]
	v_mfma_f32_16x16x32_bf16 v[24:27], v[136:139], v[184:187], v[24:27]
	v_mfma_f32_16x16x32_bf16 v[12:15], v[128:131], v[214:217], v[12:15]
	v_mfma_f32_16x16x32_bf16 v[8:11], v[136:139], v[214:217], v[8:11]
	v_mfma_f32_16x16x32_bf16 v[52:55], v[140:143], v[164:167], v[52:55]
	v_mfma_f32_16x16x32_bf16 v[48:51], v[156:159], v[164:167], v[48:51]
	v_mfma_f32_16x16x32_bf16 v[36:39], v[140:143], v[172:175], v[36:39]
	v_mfma_f32_16x16x32_bf16 v[32:35], v[156:159], v[172:175], v[32:35]
	v_mfma_f32_16x16x32_bf16 v[20:23], v[140:143], v[180:183], v[20:23]
	v_mfma_f32_16x16x32_bf16 v[16:19], v[156:159], v[180:183], v[16:19]
	v_mfma_f32_16x16x32_bf16 v[4:7], v[140:143], v[188:191], v[4:7]
	v_mfma_f32_16x16x32_bf16 v[0:3], v[156:159], v[188:191], v[0:3]
	v_mfma_f32_16x16x32_bf16 v[52:55], v[144:147], v[168:171], v[52:55]
	v_mfma_f32_16x16x32_bf16 v[48:51], v[160:163], v[168:171], v[48:51]
	v_mfma_f32_16x16x32_bf16 v[36:39], v[144:147], v[176:179], v[36:39]
	v_mfma_f32_16x16x32_bf16 v[32:35], v[160:163], v[176:179], v[32:35]
	v_mfma_f32_16x16x32_bf16 v[20:23], v[144:147], v[184:187], v[20:23]
	v_mfma_f32_16x16x32_bf16 v[16:19], v[160:163], v[184:187], v[16:19]
	v_mfma_f32_16x16x32_bf16 v[4:7], v[144:147], v[214:217], v[4:7]
	v_mfma_f32_16x16x32_bf16 v[0:3], v[160:163], v[214:217], v[0:3]
	s_setprio 0
	s_barrier
	s_add_i32 s56, s56, 2
	s_add_u32 s40, s40, 0x100
	s_addc_u32 s41, s41, 0
	s_cmp_gt_u32 s56, 61
	s_cbranch_scc0 .LBB0_965
	s_mov_b32 s57, 0x10000
	s_mov_b32 s60, 0x14000
	s_mov_b32 s30, 0x18000
	s_mov_b32 s31, 0x1c000
	s_and_b64 vcc, exec, s[10:11]
	s_cbranch_vccz .LBB0_968
	s_barrier

; #define PG8_STAGE(bufoff, gbase, voff) do { _Pragma("unroll") for (int _i = 0; _i < 2; ++_i) \
;         __builtin_amdgcn_global_load_lds((const unsigned*)((const char*)(gbase) + (voff)[_i]), (PG8_LAS unsigned*)(lds + (bufoff) + ldsw + _i * 8192), 16, 0, 0); } while (0)
; #define PG8_LDA(dst, b, h) do { _Pragma("unroll") for (int m = 0; m < 4; ++m) _Pragma("unroll") for (int k = 0; k < 2; ++k) dst[m][k] = *(const PG8_LAS bf16x8*)(lds + PG8_SA(b, h) + aoff + m * 2048 + k * 1024); } while (0)
; #define PG8_LDB(dst, b, h) do { _Pragma("unroll") for (int n = 0; n < 2; ++n) _Pragma("unroll") for (int k = 0; k < 2; ++k) dst[n][k] = *(const PG8_LAS bf16x8*)(lds + PG8_SB(b, h) + boff + n * 2048 + k * 1024); } while (0)
; #define PG8_MMA(ai, bj, At, Bt) do { __builtin_amdgcn_s_setprio(1); _Pragma("unroll") for (int m = 0; m < 4; ++m) _Pragma("unroll") for (int n = 0; n < 2; ++n) _Pragma("unroll") for (int k = 0; k < 2; ++k) \
;         acc[ai][bj][m][n] = __builtin_amdgcn_mfma_f32_16x16x32_bf16(Bt[n][k], At[m][k], acc[ai][bj][m][n], 0, 0, 0); __builtin_amdgcn_s_setprio(0); } while (0)
; #define PG8_WAIT_L(n) asm volatile("s_waitcnt lgkmcnt(" #n ")" ::: "memory")
; #define PG8_BAR __builtin_amdgcn_s_barrier()
; template <class Epi, class Sched, bool ALIGN_EPI = false, bool SP2 = false>
; __device__ __forceinline__ void gemm_phase(PG8_LAS unsigned char* lds, const Gemm g, const Sched& S, const Epi& E) {
;     ...
;             const char* a1 = cA + (size_t)(t + 1) * kstep;
;             const char* a2 = last ? nA : cA + (size_t)(t + 2) * kstep; const char* b2 = last ? nB : cB + (size_t)(t + 2) * kstep;
;             const char* a3 = a2 + kstep; const char* b3 = b2 + kstep;
;             if (last && has_next) S.a_ready(nxt);
;             if constexpr (SP2) {
;             const int rx = (relax && t == 0) ? 1 : 0;
;             PG8_STAGE(PG8_SA(1, 1), a1 + hstep, voffA); PG8_SCHED; PG8_LDB(B0, 0, 0); PG8_LDB(B1, 0, 1); PG8_SCHED; PG8_LDA(At, 0, 0);
;             PG8_WAIT_V8_UNLESS(rx); PG8_WAIT_L(0); PG8_BAR; PG8_MMA(0, 0, At, B0); PG8_MMA(0, 1, At, B1); PG8_BAR; PG8_SCHED;
;             PG8_STAGE(PG8_SB(0, 0), b2, voffB); PG8_STAGE(PG8_SB(0, 1), b2 + hstep, voffB); PG8_STAGE(PG8_SA(0, 0), a2, voffA); PG8_SCHED; PG8_LDA(At, 0, 1);
;             PG8_WAIT_V8_UNLESS(rx); PG8_WAIT_L(0); PG8_BAR; PG8_MMA(1, 0, At, B0); PG8_MMA(1, 1, At, B1); PG8_BAR; PG8_SCHED;
.LBB0_1133:
	s_add_u32 s28, s42, vcc_lo
	s_addc_u32 s29, s43, vcc_hi
	s_add_u32 s30, s28, 0x100
	s_addc_u32 s31, s29, 0
	s_add_u32 s98, s28, 0x40080
	s_addc_u32 s99, s29, 0
	s_add_u32 s65, s57, vcc_lo
	s_addc_u32 s66, s58, vcc_hi
	s_cmp_eq_u32 vcc_lo, 0
	s_cselect_b64 s[28:29], -1, 0
	s_and_b64 s[60:61], s[62:63], s[28:29]
	s_cmpk_eq_i32 vcc_lo, 0x700
	s_cselect_b32 s31, s19, s31
	s_cselect_b32 s30, s27, s30
	s_cselect_b32 s29, s17, s66
	s_cselect_b32 s28, s34, s65
	ds_read_b128 v[132:135], v128
	ds_read_b128 v[136:139], v128 offset:1024
	ds_read_b128 v[140:143], v128 offset:2048
	ds_read_b128 v[144:147], v128 offset:3072
	ds_read_b128 v[160:163], v128 offset:16384
	ds_read_b128 v[164:167], v128 offset:17408
	ds_read_b128 v[168:171], v128 offset:18432
	ds_read_b128 v[176:179], v128 offset:19456
	ds_read_b128 v[180:183], v175
	ds_read_b128 v[184:187], v175 offset:1024
	ds_read_b128 v[188:191], v175 offset:2048
	ds_read_b128 v[204:207], v175 offset:3072
	ds_read_b128 v[208:211], v175 offset:4096
	ds_read_b128 v[212:215], v175 offset:5120
	ds_read_b128 v[216:219], v175 offset:6144
	s_add_i32 m0, s41, 0xc000
	s_and_b32 s67, s60, 1
	global_load_lds_dwordx4 v148, s[98:99]
	s_add_i32 m0, s41, 0xe000
	ds_read_b128 v[220:223], v175 offset:7168
	global_load_lds_dwordx4 v152, s[98:99]
	s_cmp_lg_i32 s67, 0
	s_cbranch_scc1 .Lpg8rx10
	s_waitcnt vmcnt(8)
.Lpg8rx10:
	s_waitcnt lgkmcnt(0)
	s_setprio 1
	s_barrier
	v_mfma_f32_16x16x32_bf16 v[124:127], v[132:135], v[180:183], v[124:127]
	v_mfma_f32_16x16x32_bf16 v[120:123], v[140:143], v[180:183], v[120:123]
	v_mfma_f32_16x16x32_bf16 v[108:111], v[132:135], v[188:191], v[108:111]
	v_mfma_f32_16x16x32_bf16 v[104:107], v[140:143], v[188:191], v[104:107]
	v_mfma_f32_16x16x32_bf16 v[92:95], v[132:135], v[208:211], v[92:95]
	v_mfma_f32_16x16x32_bf16 v[88:91], v[140:143], v[208:211], v[88:91]
	v_mfma_f32_16x16x32_bf16 v[76:79], v[132:135], v[216:219], v[76:79]
	v_mfma_f32_16x16x32_bf16 v[72:75], v[140:143], v[216:219], v[72:75]
	v_mfma_f32_16x16x32_bf16 v[124:127], v[136:139], v[184:187], v[124:127]
	v_mfma_f32_16x16x32_bf16 v[120:123], v[144:147], v[184:187], v[120:123]
	v_mfma_f32_16x16x32_bf16 v[108:111], v[136:139], v[204:207], v[108:111]
	v_mfma_f32_16x16x32_bf16 v[104:107], v[144:147], v[204:207], v[104:107]
	v_mfma_f32_16x16x32_bf16 v[92:95], v[136:139], v[212:215], v[92:95]
	v_mfma_f32_16x16x32_bf16 v[88:91], v[144:147], v[212:215], v[88:91]
	v_mfma_f32_16x16x32_bf16 v[76:79], v[136:139], v[220:223], v[76:79]
	v_mfma_f32_16x16x32_bf16 v[72:75], v[144:147], v[220:223], v[72:75]
	v_mfma_f32_16x16x32_bf16 v[116:119], v[160:163], v[180:183], v[116:119]
	v_mfma_f32_16x16x32_bf16 v[112:115], v[168:171], v[180:183], v[112:115]
	v_mfma_f32_16x16x32_bf16 v[100:103], v[160:163], v[188:191], v[100:103]
	v_mfma_f32_16x16x32_bf16 v[96:99], v[168:171], v[188:191], v[96:99]
	v_mfma_f32_16x16x32_bf16 v[84:87], v[160:163], v[208:211], v[84:87]
	v_mfma_f32_16x16x32_bf16 v[80:83], v[168:171], v[208:211], v[80:83]
	v_mfma_f32_16x16x32_bf16 v[68:71], v[160:163], v[216:219], v[68:71]
	v_mfma_f32_16x16x32_bf16 v[64:67], v[168:171], v[216:219], v[64:67]
	v_mfma_f32_16x16x32_bf16 v[116:119], v[164:167], v[184:187], v[116:119]
	v_mfma_f32_16x16x32_bf16 v[112:115], v[176:179], v[184:187], v[112:115]
	v_mfma_f32_16x16x32_bf16 v[100:103], v[164:167], v[204:207], v[100:103]
	v_mfma_f32_16x16x32_bf16 v[96:99], v[176:179], v[204:207], v[96:99]
	v_mfma_f32_16x16x32_bf16 v[84:87], v[164:167], v[212:215], v[84:87]
	v_mfma_f32_16x16x32_bf16 v[80:83], v[176:179], v[212:215], v[80:83]
	v_mfma_f32_16x16x32_bf16 v[68:71], v[164:167], v[220:223], v[68:71]
	v_mfma_f32_16x16x32_bf16 v[64:67], v[176:179], v[220:223], v[64:67]
	s_setprio 0
	s_barrier
	ds_read_b128 v[180:183], v175 offset:16384
	ds_read_b128 v[184:187], v175 offset:17408
	s_add_u32 s60, s28, 0x40000
	s_addc_u32 s61, s29, 0
	s_add_i32 m0, s35, 0x10000
	ds_read_b128 v[188:191], v175 offset:18432
	global_load_lds_dwordx4 v150, s[28:29]
	s_add_i32 m0, m0, 0x2000
	ds_read_b128 v[204:207], v175 offset:19456
	global_load_lds_dwordx4 v154, s[28:29]
	s_add_i32 m0, s35, 0x14000
	ds_read_b128 v[208:211], v175 offset:20480
	global_load_lds_dwordx4 v150, s[60:61]
	s_add_i32 m0, m0, 0x2000
	ds_read_b128 v[212:215], v175 offset:21504
	global_load_lds_dwordx4 v154, s[60:61]
	s_mov_b32 m0, s41
	ds_read_b128 v[216:219], v175 offset:22528
	global_load_lds_dwordx4 v148, s[30:31]
	s_mov_b32 m0, s48
	ds_read_b128 v[220:223], v175 offset:23552
	global_load_lds_dwordx4 v152, s[30:31]
	s_cmp_lg_i32 s67, 0
	s_cbranch_scc1 .Lpg8rx11
	s_waitcnt vmcnt(8)
; #define PG8_STAGE(bufoff, gbase, voff) do { _Pragma("unroll") for (int _i = 0; _i < 2; ++_i) \
;         __builtin_amdgcn_global_load_lds((const unsigned*)((const char*)(gbase) + (voff)[_i]), (PG8_LAS unsigned*)(lds + (bufoff) + ldsw + _i * 8192), 16, 0, 0); } while (0)
; #define PG8_LDA(dst, b, h) do { _Pragma("unroll") for (int m = 0; m < 4; ++m) _Pragma("unroll") for (int k = 0; k < 2; ++k) dst[m][k] = *(const PG8_LAS bf16x8*)(lds + PG8_SA(b, h) + aoff + m * 2048 + k * 1024); } while (0)
; #define PG8_LDB(dst, b, h) do { _Pragma("unroll") for (int n = 0; n < 2; ++n) _Pragma("unroll") for (int k = 0; k < 2; ++k) dst[n][k] = *(const PG8_LAS bf16x8*)(lds + PG8_SB(b, h) + boff + n * 2048 + k * 1024); } while (0)
; #define PG8_MMA(ai, bj, At, Bt) do { __builtin_amdgcn_s_setprio(1); _Pragma("unroll") for (int m = 0; m < 4; ++m) _Pragma("unroll") for (int n = 0; n < 2; ++n) _Pragma("unroll") for (int k = 0; k < 2; ++k) \
;         acc[ai][bj][m][n] = __builtin_amdgcn_mfma_f32_16x16x32_bf16(Bt[n][k], At[m][k], acc[ai][bj][m][n], 0, 0, 0); __builtin_amdgcn_s_setprio(0); } while (0)
; #define PG8_WAIT_V(n) asm volatile("s_waitcnt vmcnt(" #n ")" ::: "memory")
; #define PG8_WAIT_L(n) asm volatile("s_waitcnt lgkmcnt(" #n ")" ::: "memory")
; #define PG8_WAIT_V8_UNLESS(flag) asm volatile("s_cmp_lg_i32 %0, 0\n\ts_cbranch_scc1 .Lpg8rx%=\n\ts_waitcnt vmcnt(8)\n.Lpg8rx%=:" :: "s"(__builtin_amdgcn_readfirstlane(flag)) : "scc", "memory")
; #define PG8_BAR __builtin_amdgcn_s_barrier()
; #define PG8_SCHED __builtin_amdgcn_sched_barrier(0)
; template <class Epi, class Sched, bool ALIGN_EPI = false, bool SP2 = false>
; __device__ __forceinline__ void gemm_phase(PG8_LAS unsigned char* lds, const Gemm g, const Sched& S, const Epi& E) {
;     ...
;             PG8_WAIT_V8_UNLESS(rx); PG8_WAIT_L(0); PG8_BAR; PG8_MMA(1, 0, At, B0); PG8_MMA(1, 1, At, B1); PG8_BAR; PG8_SCHED;
;             PG8_STAGE(PG8_SA(0, 1), a2 + hstep, voffA); PG8_SCHED; PG8_LDB(B0, 1, 0); PG8_LDB(B1, 1, 1); PG8_SCHED; PG8_LDA(At, 1, 0);
;             PG8_WAIT_V(8); PG8_WAIT_L(0); PG8_BAR; PG8_MMA(0, 0, At, B0); PG8_MMA(0, 1, At, B1); PG8_BAR; PG8_SCHED;
.Lpg8rx11:
	s_waitcnt lgkmcnt(0)
	s_setprio 1
	s_barrier
	v_mfma_f32_16x16x32_bf16 v[60:63], v[132:135], v[180:183], v[60:63]
	v_mfma_f32_16x16x32_bf16 v[56:59], v[140:143], v[180:183], v[56:59]
	v_mfma_f32_16x16x32_bf16 v[44:47], v[132:135], v[188:191], v[44:47]
	v_mfma_f32_16x16x32_bf16 v[40:43], v[140:143], v[188:191], v[40:43]
	v_mfma_f32_16x16x32_bf16 v[28:31], v[132:135], v[208:211], v[28:31]
	v_mfma_f32_16x16x32_bf16 v[24:27], v[140:143], v[208:211], v[24:27]
	v_mfma_f32_16x16x32_bf16 v[12:15], v[132:135], v[216:219], v[12:15]
	v_mfma_f32_16x16x32_bf16 v[8:11], v[140:143], v[216:219], v[8:11]
	v_mfma_f32_16x16x32_bf16 v[60:63], v[136:139], v[184:187], v[60:63]
	v_mfma_f32_16x16x32_bf16 v[56:59], v[144:147], v[184:187], v[56:59]
	v_mfma_f32_16x16x32_bf16 v[44:47], v[136:139], v[204:207], v[44:47]
	v_mfma_f32_16x16x32_bf16 v[40:43], v[144:147], v[204:207], v[40:43]
	v_mfma_f32_16x16x32_bf16 v[28:31], v[136:139], v[212:215], v[28:31]
	v_mfma_f32_16x16x32_bf16 v[24:27], v[144:147], v[212:215], v[24:27]
	v_mfma_f32_16x16x32_bf16 v[12:15], v[136:139], v[220:223], v[12:15]
	v_mfma_f32_16x16x32_bf16 v[8:11], v[144:147], v[220:223], v[8:11]
	v_mfma_f32_16x16x32_bf16 v[52:55], v[160:163], v[180:183], v[52:55]
	v_mfma_f32_16x16x32_bf16 v[48:51], v[168:171], v[180:183], v[48:51]
	v_mfma_f32_16x16x32_bf16 v[36:39], v[160:163], v[188:191], v[36:39]
	v_mfma_f32_16x16x32_bf16 v[32:35], v[168:171], v[188:191], v[32:35]
	v_mfma_f32_16x16x32_bf16 v[20:23], v[160:163], v[208:211], v[20:23]
	v_mfma_f32_16x16x32_bf16 v[16:19], v[168:171], v[208:211], v[16:19]
	v_mfma_f32_16x16x32_bf16 v[4:7], v[160:163], v[216:219], v[4:7]
	v_mfma_f32_16x16x32_bf16 v[0:3], v[168:171], v[216:219], v[0:3]
	v_mfma_f32_16x16x32_bf16 v[52:55], v[164:167], v[184:187], v[52:55]
	v_mfma_f32_16x16x32_bf16 v[48:51], v[176:179], v[184:187], v[48:51]
	v_mfma_f32_16x16x32_bf16 v[36:39], v[164:167], v[204:207], v[36:39]
	v_mfma_f32_16x16x32_bf16 v[32:35], v[176:179], v[204:207], v[32:35]
	v_mfma_f32_16x16x32_bf16 v[20:23], v[164:167], v[212:215], v[20:23]
	v_mfma_f32_16x16x32_bf16 v[16:19], v[176:179], v[212:215], v[16:19]
	v_mfma_f32_16x16x32_bf16 v[4:7], v[164:167], v[220:223], v[4:7]
	v_mfma_f32_16x16x32_bf16 v[0:3], v[176:179], v[220:223], v[0:3]
	s_setprio 0
	s_barrier
	s_mov_b64 s[98:99], s[30:31]
	s_add_u32 s100, s30, 0x40000
	s_addc_u32 s101, s31, 0
	ds_read_b128 v[132:135], v128 offset:32768
	ds_read_b128 v[136:139], v128 offset:33792
	ds_read_b128 v[140:143], v128 offset:34816
	ds_read_b128 v[144:147], v128 offset:35840
	ds_read_b128 v[160:163], v128 offset:49152
	ds_read_b128 v[164:167], v128 offset:50176
	ds_read_b128 v[168:171], v128 offset:51200
	ds_read_b128 v[176:179], v128 offset:52224
	ds_read_b128 v[180:183], v175 offset:32768
	ds_read_b128 v[184:187], v175 offset:33792
	ds_read_b128 v[188:191], v175 offset:34816
	ds_read_b128 v[204:207], v175 offset:35840
	ds_read_b128 v[208:211], v175 offset:36864
	ds_read_b128 v[212:215], v175 offset:37888
	s_mov_b32 m0, s50
	ds_read_b128 v[216:219], v175 offset:38912
	global_load_lds_dwordx4 v148, s[100:101]
	s_mov_b32 m0, s51
	ds_read_b128 v[220:223], v175 offset:39936
	global_load_lds_dwordx4 v152, s[100:101]
	s_waitcnt vmcnt(8) lgkmcnt(0)
	s_setprio 1
	s_barrier
	v_mfma_f32_16x16x32_bf16 v[124:127], v[132:135], v[180:183], v[124:127]
	v_mfma_f32_16x16x32_bf16 v[120:123], v[140:143], v[180:183], v[120:123]
	v_mfma_f32_16x16x32_bf16 v[108:111], v[132:135], v[188:191], v[108:111]
	v_mfma_f32_16x16x32_bf16 v[104:107], v[140:143], v[188:191], v[104:107]
	v_mfma_f32_16x16x32_bf16 v[92:95], v[132:135], v[208:211], v[92:95]
	v_mfma_f32_16x16x32_bf16 v[88:91], v[140:143], v[208:211], v[88:91]
	v_mfma_f32_16x16x32_bf16 v[76:79], v[132:135], v[216:219], v[76:79]
	v_mfma_f32_16x16x32_bf16 v[72:75], v[140:143], v[216:219], v[72:75]
	v_mfma_f32_16x16x32_bf16 v[124:127], v[136:139], v[184:187], v[124:127]
	v_mfma_f32_16x16x32_bf16 v[120:123], v[144:147], v[184:187], v[120:123]
	v_mfma_f32_16x16x32_bf16 v[108:111], v[136:139], v[204:207], v[108:111]
	v_mfma_f32_16x16x32_bf16 v[104:107], v[144:147], v[204:207], v[104:107]
	v_mfma_f32_16x16x32_bf16 v[92:95], v[136:139], v[212:215], v[92:95]
	v_mfma_f32_16x16x32_bf16 v[88:91], v[144:147], v[212:215], v[88:91]
	v_mfma_f32_16x16x32_bf16 v[76:79], v[136:139], v[220:223], v[76:79]
	v_mfma_f32_16x16x32_bf16 v[72:75], v[144:147], v[220:223], v[72:75]
	v_mfma_f32_16x16x32_bf16 v[116:119], v[160:163], v[180:183], v[116:119]
	v_mfma_f32_16x16x32_bf16 v[112:115], v[168:171], v[180:183], v[112:115]
	v_mfma_f32_16x16x32_bf16 v[100:103], v[160:163], v[188:191], v[100:103]
	v_mfma_f32_16x16x32_bf16 v[96:99], v[168:171], v[188:191], v[96:99]
	v_mfma_f32_16x16x32_bf16 v[84:87], v[160:163], v[208:211], v[84:87]
	v_mfma_f32_16x16x32_bf16 v[80:83], v[168:171], v[208:211], v[80:83]
	v_mfma_f32_16x16x32_bf16 v[68:71], v[160:163], v[216:219], v[68:71]
	v_mfma_f32_16x16x32_bf16 v[64:67], v[168:171], v[216:219], v[64:67]
	v_mfma_f32_16x16x32_bf16 v[116:119], v[164:167], v[184:187], v[116:119]
	v_mfma_f32_16x16x32_bf16 v[112:115], v[176:179], v[184:187], v[112:115]
	v_mfma_f32_16x16x32_bf16 v[100:103], v[164:167], v[204:207], v[100:103]
	v_mfma_f32_16x16x32_bf16 v[96:99], v[176:179], v[204:207], v[96:99]
	v_mfma_f32_16x16x32_bf16 v[84:87], v[164:167], v[212:215], v[84:87]
	v_mfma_f32_16x16x32_bf16 v[80:83], v[176:179], v[212:215], v[80:83]
	v_mfma_f32_16x16x32_bf16 v[68:71], v[164:167], v[220:223], v[68:71]
	v_mfma_f32_16x16x32_bf16 v[64:67], v[176:179], v[220:223], v[64:67]
	s_setprio 0
	s_barrier
; #define PG8_STAGE(bufoff, gbase, voff) do { _Pragma("unroll") for (int _i = 0; _i < 2; ++_i) \
;         __builtin_amdgcn_global_load_lds((const unsigned*)((const char*)(gbase) + (voff)[_i]), (PG8_LAS unsigned*)(lds + (bufoff) + ldsw + _i * 8192), 16, 0, 0); } while (0)
; #define PG8_LDA(dst, b, h) do { _Pragma("unroll") for (int m = 0; m < 4; ++m) _Pragma("unroll") for (int k = 0; k < 2; ++k) dst[m][k] = *(const PG8_LAS bf16x8*)(lds + PG8_SA(b, h) + aoff + m * 2048 + k * 1024); } while (0)
; #define PG8_MMA(ai, bj, At, Bt) do { __builtin_amdgcn_s_setprio(1); _Pragma("unroll") for (int m = 0; m < 4; ++m) _Pragma("unroll") for (int n = 0; n < 2; ++n) _Pragma("unroll") for (int k = 0; k < 2; ++k) \
;         acc[ai][bj][m][n] = __builtin_amdgcn_mfma_f32_16x16x32_bf16(Bt[n][k], At[m][k], acc[ai][bj][m][n], 0, 0, 0); __builtin_amdgcn_s_setprio(0); } while (0)
; #define PG8_WAIT_V(n) asm volatile("s_waitcnt vmcnt(" #n ")" ::: "memory")
; #define PG8_WAIT_L(n) asm volatile("s_waitcnt lgkmcnt(" #n ")" ::: "memory")
; #define PG8_BAR __builtin_amdgcn_s_barrier()
; #define PG8_SCHED __builtin_amdgcn_sched_barrier(0)
; template <class Epi, class Sched, bool ALIGN_EPI = false, bool SP2 = false>
; __device__ __forceinline__ void gemm_phase(PG8_LAS unsigned char* lds, const Gemm g, const Sched& S, const Epi& E) {
;     ...
;             PG8_STAGE(PG8_SB(1, 0), b3, voffB); PG8_STAGE(PG8_SB(1, 1), b3 + hstep, voffB); PG8_STAGE(PG8_SA(1, 0), a3, voffA); PG8_SCHED; PG8_LDA(At, 1, 1);
;             PG8_WAIT_V(8); PG8_WAIT_L(0); PG8_BAR; PG8_MMA(1, 0, At, B0); PG8_MMA(1, 1, At, B1); PG8_BAR; PG8_SCHED;
;     ...
;         if constexpr (ALIGN_EPI) { if (wr == 0) PG8_BAR; }
	ds_read_b128 v[180:183], v175 offset:49152
	ds_read_b128 v[184:187], v175 offset:50176
	s_add_u32 s100, s28, 0x80
	s_addc_u32 s101, s29, 0
	s_add_u32 s28, s28, 0x40080
	s_addc_u32 s29, s29, 0
	s_add_u32 s98, s98, 0x80
	s_addc_u32 s99, s99, 0
	s_add_i32 m0, s35, 0x18000
	ds_read_b128 v[188:191], v175 offset:51200
	global_load_lds_dwordx4 v150, s[100:101]
	s_add_i32 m0, m0, 0x2000
	ds_read_b128 v[204:207], v175 offset:52224
	global_load_lds_dwordx4 v154, s[100:101]
	s_add_i32 m0, s35, 0x1c000
	ds_read_b128 v[208:211], v175 offset:53248
	global_load_lds_dwordx4 v150, s[28:29]
	s_add_i32 m0, m0, 0x2000
	ds_read_b128 v[212:215], v175 offset:54272
	global_load_lds_dwordx4 v154, s[28:29]
	s_mov_b32 m0, s52
	ds_read_b128 v[216:219], v175 offset:55296
	global_load_lds_dwordx4 v148, s[98:99]
	s_mov_b32 m0, s53
	ds_read_b128 v[220:223], v175 offset:56320
	global_load_lds_dwordx4 v152, s[98:99]
	s_waitcnt vmcnt(8) lgkmcnt(0)
	s_setprio 1
	s_barrier
	v_mfma_f32_16x16x32_bf16 v[60:63], v[132:135], v[180:183], v[60:63]
	v_mfma_f32_16x16x32_bf16 v[56:59], v[140:143], v[180:183], v[56:59]
	v_mfma_f32_16x16x32_bf16 v[44:47], v[132:135], v[188:191], v[44:47]
	v_mfma_f32_16x16x32_bf16 v[40:43], v[140:143], v[188:191], v[40:43]
	v_mfma_f32_16x16x32_bf16 v[28:31], v[132:135], v[208:211], v[28:31]
	v_mfma_f32_16x16x32_bf16 v[24:27], v[140:143], v[208:211], v[24:27]
	v_mfma_f32_16x16x32_bf16 v[12:15], v[132:135], v[216:219], v[12:15]
	v_mfma_f32_16x16x32_bf16 v[8:11], v[140:143], v[216:219], v[8:11]
	v_mfma_f32_16x16x32_bf16 v[60:63], v[136:139], v[184:187], v[60:63]
	v_mfma_f32_16x16x32_bf16 v[56:59], v[144:147], v[184:187], v[56:59]
	v_mfma_f32_16x16x32_bf16 v[44:47], v[136:139], v[204:207], v[44:47]
	v_mfma_f32_16x16x32_bf16 v[40:43], v[144:147], v[204:207], v[40:43]
	v_mfma_f32_16x16x32_bf16 v[28:31], v[136:139], v[212:215], v[28:31]
	v_mfma_f32_16x16x32_bf16 v[24:27], v[144:147], v[212:215], v[24:27]
	v_mfma_f32_16x16x32_bf16 v[12:15], v[136:139], v[220:223], v[12:15]
	v_mfma_f32_16x16x32_bf16 v[8:11], v[144:147], v[220:223], v[8:11]
	v_mfma_f32_16x16x32_bf16 v[52:55], v[160:163], v[180:183], v[52:55]
	v_mfma_f32_16x16x32_bf16 v[48:51], v[168:171], v[180:183], v[48:51]
	v_mfma_f32_16x16x32_bf16 v[36:39], v[160:163], v[188:191], v[36:39]
	v_mfma_f32_16x16x32_bf16 v[32:35], v[168:171], v[188:191], v[32:35]
	v_mfma_f32_16x16x32_bf16 v[20:23], v[160:163], v[208:211], v[20:23]
	v_mfma_f32_16x16x32_bf16 v[16:19], v[168:171], v[208:211], v[16:19]
	v_mfma_f32_16x16x32_bf16 v[4:7], v[160:163], v[216:219], v[4:7]
	v_mfma_f32_16x16x32_bf16 v[0:3], v[168:171], v[216:219], v[0:3]
	v_mfma_f32_16x16x32_bf16 v[52:55], v[164:167], v[184:187], v[52:55]
	v_mfma_f32_16x16x32_bf16 v[48:51], v[176:179], v[184:187], v[48:51]
	v_mfma_f32_16x16x32_bf16 v[36:39], v[164:167], v[204:207], v[36:39]
	v_mfma_f32_16x16x32_bf16 v[32:35], v[176:179], v[204:207], v[32:35]
	v_mfma_f32_16x16x32_bf16 v[20:23], v[164:167], v[212:215], v[20:23]
	v_mfma_f32_16x16x32_bf16 v[16:19], v[176:179], v[212:215], v[16:19]
	v_mfma_f32_16x16x32_bf16 v[4:7], v[164:167], v[220:223], v[4:7]
	v_mfma_f32_16x16x32_bf16 v[0:3], v[176:179], v[220:223], v[0:3]
	s_setprio 0
	s_barrier
	s_add_i32 s59, s59, 2
	s_add_u32 vcc_lo, vcc_lo, 0x100
	s_addc_u32 vcc_hi, vcc_hi, 0
	s_cmp_gt_u32 s59, 13
	s_cbranch_scc0 .LBB0_1133
	s_mov_b32 s65, 0x10000
	s_mov_b32 s66, 0x14000
	s_mov_b32 s30, 0x18000
	s_mov_b32 s31, 0x1c000
	s_and_b64 vcc, exec, s[14:15]
	s_cbranch_vccz .LBB0_1136
	s_barrier
